# MLA: cost-weighted VALU spacing around MFMAs with transcendental weight 5/3 (was 2.0)
# baseline (speedup 1.0000x reference)
.Lmla_loop:
	v_exp_f32_e32 v34, v34
	v_exp_f32_e32 v35, v35
	v_exp_f32_e32 v36, v36
	s_waitcnt lgkmcnt(4)
	v_mfma_f32_32x32x16_bf16 v[66:81], v[138:141], v[98:101], v[122:137]
	ds_read_b128 v[138:141], v220 offset:13408
	v_exp_f32_e32 v37, v37
	v_add_f32_e32 v231, v231, v34
	v_add_f32_e32 v232, v232, v35
	v_exp_f32_e32 v38, v38
	v_mfma_f32_32x32x16_bf16 v[82:97], v[142:145], v[98:101], v[122:137]
	ds_read_b128 v[142:145], v220 offset:20064
	v_exp_f32_e32 v39, v39
	v_add_f32_e32 v231, v231, v36
	v_add_f32_e32 v232, v232, v37
	v_exp_f32_e32 v40, v40
	s_waitcnt lgkmcnt(4)
	v_mfma_f32_32x32x16_bf16 v[66:81], v[146:149], v[102:105], v[66:81]
	ds_read_b128 v[146:149], v220 offset:13440
	global_load_dwordx4 v[200:203], v226, s[4:5]
	global_load_dwordx4 v[204:207], v227, s[4:5]
	global_load_dwordx4 v[208:211], v228, s[4:5]
	s_add_u32 s4, s4, 0x6000
	s_addc_u32 s5, s5, 0
	global_load_dwordx4 v[212:215], v229, s[10:11]
	s_add_u32 s10, s10, 0x80
	s_addc_u32 s11, s11, 0
	v_exp_f32_e32 v41, v41
	v_add_f32_e32 v231, v231, v38
	v_add_f32_e32 v232, v232, v39
	v_mfma_f32_32x32x16_bf16 v[82:97], v[150:153], v[102:105], v[82:97]
	ds_read_b128 v[150:153], v220 offset:20096
	v_add_f32_e32 v231, v231, v40
	v_add_f32_e32 v232, v232, v41
	v_cvt_pk_bf16_f32 v34, v34, v35
	v_cvt_pk_bf16_f32 v35, v36, v37
	v_cvt_pk_bf16_f32 v36, v38, v39
	s_waitcnt lgkmcnt(4)
	v_mfma_f32_32x32x16_bf16 v[66:81], v[154:157], v[106:109], v[66:81]
	ds_read_b128 v[154:157], v220 offset:13472
	v_cvt_pk_bf16_f32 v37, v40, v41
	v_exp_f32_e32 v42, v42
	v_exp_f32_e32 v43, v43
	v_exp_f32_e32 v44, v44
	v_mfma_f32_32x32x16_bf16 v[82:97], v[158:161], v[106:109], v[82:97]
	ds_read_b128 v[158:161], v220 offset:20128
	v_exp_f32_e32 v45, v45
	v_add_f32_e32 v231, v231, v42
	v_add_f32_e32 v232, v232, v43
	s_waitcnt lgkmcnt(4)
	v_mfma_f32_32x32x16_bf16 v[66:81], v[138:141], v[110:113], v[66:81]
	ds_read_b128 v[162:165], v221 offset:0
	v_exp_f32_e32 v46, v46
	v_exp_f32_e32 v47, v47
	v_add_f32_e32 v231, v231, v44
	v_add_f32_e32 v232, v232, v45
	v_mfma_f32_32x32x16_bf16 v[82:97], v[142:145], v[110:113], v[82:97]
	ds_read_b128 v[166:169], v221 offset:4608
	v_exp_f32_e32 v48, v48
	v_exp_f32_e32 v49, v49
	v_add_f32_e32 v231, v231, v46
	s_waitcnt lgkmcnt(4)
	v_mfma_f32_32x32x16_bf16 v[66:81], v[146:149], v[114:117], v[66:81]
	ds_read_b128 v[170:173], v221 offset:32
	v_add_f32_e32 v232, v232, v47
	v_add_f32_e32 v231, v231, v48
	v_add_f32_e32 v232, v232, v49
	v_cvt_pk_bf16_f32 v42, v42, v43
	v_cvt_pk_bf16_f32 v43, v44, v45
	v_mfma_f32_32x32x16_bf16 v[82:97], v[150:153], v[114:117], v[82:97]
	ds_read_b128 v[174:177], v221 offset:4640
	v_cvt_pk_bf16_f32 v44, v46, v47
	v_cvt_pk_bf16_f32 v45, v48, v49
	v_exp_f32_e32 v50, v50
	v_exp_f32_e32 v51, v51
	s_waitcnt lgkmcnt(4)
	v_mfma_f32_32x32x16_bf16 v[66:81], v[154:157], v[118:121], v[66:81]
	ds_read_b128 v[180:183], v221 offset:64
	v_exp_f32_e32 v52, v52
	v_exp_f32_e32 v53, v53
	v_add_f32_e32 v231, v231, v50
	v_mfma_f32_32x32x16_bf16 v[82:97], v[158:161], v[118:121], v[82:97]
	ds_read_b128 v[184:187], v221 offset:4672
	v_add_f32_e32 v232, v232, v51
	v_exp_f32_e32 v54, v54
	v_exp_f32_e32 v55, v55
	v_add_f32_e32 v231, v231, v52
	s_waitcnt lgkmcnt(4)
	v_mfma_f32_32x32x16_bf16 v[2:17], v[162:165], v[34:37], v[2:17]
	ds_read_b128 v[188:191], v221 offset:96
	v_add_f32_e32 v232, v232, v53
	v_exp_f32_e32 v56, v56
	v_exp_f32_e32 v57, v57
	v_mfma_f32_32x32x16_bf16 v[18:33], v[166:169], v[34:37], v[18:33]
	ds_read_b128 v[192:195], v221 offset:4704
	v_add_f32_e32 v231, v231, v54
	v_add_f32_e32 v232, v232, v55
	v_add_f32_e32 v231, v231, v56
	v_add_f32_e32 v232, v232, v57
	v_cvt_pk_bf16_f32 v50, v50, v51
	s_waitcnt lgkmcnt(4)
	v_mfma_f32_32x32x16_bf16 v[2:17], v[170:173], v[42:45], v[2:17]
	v_cvt_pk_bf16_f32 v51, v52, v53
	v_cvt_pk_bf16_f32 v52, v54, v55
	v_cvt_pk_bf16_f32 v53, v56, v57
	v_exp_f32_e32 v58, v58
	v_mfma_f32_32x32x16_bf16 v[18:33], v[174:177], v[42:45], v[18:33]
	s_waitcnt vmcnt(4)
	ds_write_b64 v225, v[216:217] offset:18432
	ds_write_b64 v225, v[218:219] offset:18448
	v_exp_f32_e32 v59, v59
	v_exp_f32_e32 v60, v60
	v_exp_f32_e32 v61, v61
	s_waitcnt lgkmcnt(4)
	v_mfma_f32_32x32x16_bf16 v[2:17], v[180:183], v[50:53], v[2:17]
	v_add_f32_e32 v231, v231, v58
	v_add_f32_e32 v232, v232, v59
	v_exp_f32_e32 v62, v62
	v_exp_f32_e32 v63, v63
	v_mfma_f32_32x32x16_bf16 v[18:33], v[184:187], v[50:53], v[18:33]
	v_add_f32_e32 v231, v231, v60
	v_add_f32_e32 v232, v232, v61
	v_exp_f32_e32 v64, v64
	v_exp_f32_e32 v65, v65
	v_add_f32_e32 v231, v231, v62
	v_add_f32_e32 v232, v232, v63
	v_add_f32_e32 v231, v231, v64
	v_add_f32_e32 v232, v232, v65
	v_cvt_pk_bf16_f32 v58, v58, v59
	v_cvt_pk_bf16_f32 v59, v60, v61
	v_cvt_pk_bf16_f32 v60, v62, v63
	v_cvt_pk_bf16_f32 v61, v64, v65
	s_waitcnt lgkmcnt(2)
	s_nop 0
	v_mfma_f32_32x32x16_bf16 v[2:17], v[188:191], v[58:61], v[2:17]
	v_mfma_f32_32x32x16_bf16 v[18:33], v[192:195], v[58:61], v[18:33]
	ds_read_b128 v[138:141], v220 offset:26624
	ds_read_b128 v[142:145], v220 offset:33280
	ds_read_b128 v[146:149], v220 offset:26656
	ds_read_b128 v[150:153], v220 offset:33312
	ds_read_b128 v[154:157], v220 offset:26688
	ds_read_b128 v[158:161], v220 offset:33344
	s_waitcnt lgkmcnt(6)
	s_barrier
	v_exp_f32_e32 v66, v66
	v_exp_f32_e32 v67, v67
	v_exp_f32_e32 v68, v68
	s_waitcnt lgkmcnt(4)
	v_mfma_f32_32x32x16_bf16 v[34:49], v[138:141], v[98:101], v[122:137]
	ds_read_b128 v[138:141], v220 offset:26720
	v_exp_f32_e32 v69, v69
	v_add_f32_e32 v231, v231, v66
	v_add_f32_e32 v232, v232, v67
	v_exp_f32_e32 v70, v70
	v_mfma_f32_32x32x16_bf16 v[50:65], v[142:145], v[98:101], v[122:137]
	ds_read_b128 v[142:145], v220 offset:33376
	v_exp_f32_e32 v71, v71
	v_add_f32_e32 v231, v231, v68
	v_add_f32_e32 v232, v232, v69
	v_exp_f32_e32 v72, v72
	s_waitcnt lgkmcnt(4)
	v_mfma_f32_32x32x16_bf16 v[34:49], v[146:149], v[102:105], v[34:49]
	ds_read_b128 v[146:149], v220 offset:26752
	global_load_dwordx4 v[216:219], v229, s[10:11]
	s_add_u32 s10, s10, 0x80
	s_addc_u32 s11, s11, 0
	v_exp_f32_e32 v73, v73
	v_add_f32_e32 v231, v231, v70
	v_add_f32_e32 v232, v232, v71
	v_mfma_f32_32x32x16_bf16 v[50:65], v[150:153], v[102:105], v[50:65]
	ds_read_b128 v[150:153], v220 offset:33408
	v_add_f32_e32 v231, v231, v72
	v_add_f32_e32 v232, v232, v73
	v_cvt_pk_bf16_f32 v66, v66, v67
	v_cvt_pk_bf16_f32 v67, v68, v69
	v_cvt_pk_bf16_f32 v68, v70, v71
	s_waitcnt lgkmcnt(4)
	v_mfma_f32_32x32x16_bf16 v[34:49], v[154:157], v[106:109], v[34:49]
	ds_read_b128 v[154:157], v220 offset:26784
	v_cvt_pk_bf16_f32 v69, v72, v73
	v_exp_f32_e32 v74, v74
	v_exp_f32_e32 v75, v75
	v_exp_f32_e32 v76, v76
	v_mfma_f32_32x32x16_bf16 v[50:65], v[158:161], v[106:109], v[50:65]
	ds_read_b128 v[158:161], v220 offset:33440
	v_exp_f32_e32 v77, v77
	v_add_f32_e32 v231, v231, v74
	v_add_f32_e32 v232, v232, v75
	s_waitcnt lgkmcnt(4)
	v_mfma_f32_32x32x16_bf16 v[34:49], v[138:141], v[110:113], v[34:49]
	ds_read_b128 v[162:165], v221 offset:9216
	v_exp_f32_e32 v78, v78
	v_exp_f32_e32 v79, v79
	v_add_f32_e32 v231, v231, v76
	v_add_f32_e32 v232, v232, v77
	v_mfma_f32_32x32x16_bf16 v[50:65], v[142:145], v[110:113], v[50:65]
	ds_read_b128 v[166:169], v221 offset:13824
	v_exp_f32_e32 v80, v80
	v_exp_f32_e32 v81, v81
	v_add_f32_e32 v231, v231, v78
	s_waitcnt lgkmcnt(4)
	v_mfma_f32_32x32x16_bf16 v[34:49], v[146:149], v[114:117], v[34:49]
	ds_read_b128 v[170:173], v221 offset:9248
	v_add_f32_e32 v232, v232, v79
	v_add_f32_e32 v231, v231, v80
	v_add_f32_e32 v232, v232, v81
	v_cvt_pk_bf16_f32 v74, v74, v75
	v_cvt_pk_bf16_f32 v75, v76, v77
	v_mfma_f32_32x32x16_bf16 v[50:65], v[150:153], v[114:117], v[50:65]
	ds_read_b128 v[174:177], v221 offset:13856
	v_cvt_pk_bf16_f32 v76, v78, v79
	v_cvt_pk_bf16_f32 v77, v80, v81
	v_exp_f32_e32 v82, v82
	v_exp_f32_e32 v83, v83
	s_waitcnt lgkmcnt(4)
	v_mfma_f32_32x32x16_bf16 v[34:49], v[154:157], v[118:121], v[34:49]
	ds_read_b128 v[180:183], v221 offset:9280
	v_exp_f32_e32 v84, v84
	v_exp_f32_e32 v85, v85
	v_add_f32_e32 v231, v231, v82
	v_mfma_f32_32x32x16_bf16 v[50:65], v[158:161], v[118:121], v[50:65]
	ds_read_b128 v[184:187], v221 offset:13888
	v_add_f32_e32 v232, v232, v83
	v_exp_f32_e32 v86, v86
	v_exp_f32_e32 v87, v87
	v_add_f32_e32 v231, v231, v84
	s_waitcnt lgkmcnt(4)
	v_mfma_f32_32x32x16_bf16 v[2:17], v[162:165], v[66:69], v[2:17]
	ds_read_b128 v[188:191], v221 offset:9312
	v_add_f32_e32 v232, v232, v85
	v_exp_f32_e32 v88, v88
	v_exp_f32_e32 v89, v89
	v_mfma_f32_32x32x16_bf16 v[18:33], v[166:169], v[66:69], v[18:33]
	ds_read_b128 v[192:195], v221 offset:13920
	v_add_f32_e32 v231, v231, v86
	v_add_f32_e32 v232, v232, v87
	v_add_f32_e32 v231, v231, v88
	v_add_f32_e32 v232, v232, v89
	v_cvt_pk_bf16_f32 v82, v82, v83
	s_waitcnt lgkmcnt(4)
	v_mfma_f32_32x32x16_bf16 v[2:17], v[170:173], v[74:77], v[2:17]
	v_cvt_pk_bf16_f32 v83, v84, v85
	v_cvt_pk_bf16_f32 v84, v86, v87
	v_cvt_pk_bf16_f32 v85, v88, v89
	v_exp_f32_e32 v90, v90
	v_mfma_f32_32x32x16_bf16 v[18:33], v[174:177], v[74:77], v[18:33]
	s_waitcnt vmcnt(1)
	ds_write_b128 v222, v[200:203] offset:0
	ds_write_b128 v223, v[204:207] offset:0
	ds_write_b128 v224, v[208:211] offset:0
	ds_write_b64 v225, v[212:213] offset:27648
	ds_write_b64 v225, v[214:215] offset:27664
	v_exp_f32_e32 v91, v91
	v_exp_f32_e32 v92, v92
	v_exp_f32_e32 v93, v93
	s_waitcnt lgkmcnt(7)
	v_mfma_f32_32x32x16_bf16 v[2:17], v[180:183], v[82:85], v[2:17]
	v_add_f32_e32 v231, v231, v90
	v_add_f32_e32 v232, v232, v91
	v_exp_f32_e32 v94, v94
	v_exp_f32_e32 v95, v95
	v_mfma_f32_32x32x16_bf16 v[18:33], v[184:187], v[82:85], v[18:33]
	v_add_f32_e32 v231, v231, v92
	v_add_f32_e32 v232, v232, v93
	v_exp_f32_e32 v96, v96
	v_exp_f32_e32 v97, v97
	v_add_f32_e32 v231, v231, v94
	v_add_f32_e32 v232, v232, v95
	v_add_f32_e32 v231, v231, v96
	v_add_f32_e32 v232, v232, v97
	v_cvt_pk_bf16_f32 v90, v90, v91
	v_cvt_pk_bf16_f32 v91, v92, v93
	v_cvt_pk_bf16_f32 v92, v94, v95
	v_cvt_pk_bf16_f32 v93, v96, v97
	s_waitcnt lgkmcnt(5)
	s_nop 0
	v_mfma_f32_32x32x16_bf16 v[2:17], v[188:191], v[90:93], v[2:17]
	v_mfma_f32_32x32x16_bf16 v[18:33], v[192:195], v[90:93], v[18:33]
	ds_read_b128 v[138:141], v220 offset:39936
	ds_read_b128 v[142:145], v220 offset:46592
	ds_read_b128 v[146:149], v220 offset:39968
	ds_read_b128 v[150:153], v220 offset:46624
	ds_read_b128 v[154:157], v220 offset:40000
	ds_read_b128 v[158:161], v220 offset:46656
	s_waitcnt lgkmcnt(6)
	s_barrier
	v_exp_f32_e32 v34, v34
	v_exp_f32_e32 v35, v35
	v_exp_f32_e32 v36, v36
	s_waitcnt lgkmcnt(4)
	v_mfma_f32_32x32x16_bf16 v[66:81], v[138:141], v[98:101], v[122:137]
	ds_read_b128 v[138:141], v220 offset:40032
	v_exp_f32_e32 v37, v37
	v_add_f32_e32 v231, v231, v34
	v_add_f32_e32 v232, v232, v35
	v_exp_f32_e32 v38, v38
	v_mfma_f32_32x32x16_bf16 v[82:97], v[142:145], v[98:101], v[122:137]
	ds_read_b128 v[142:145], v220 offset:46688
	v_exp_f32_e32 v39, v39
	v_add_f32_e32 v231, v231, v36
	v_add_f32_e32 v232, v232, v37
	v_exp_f32_e32 v40, v40
	s_waitcnt lgkmcnt(4)
	v_mfma_f32_32x32x16_bf16 v[66:81], v[146:149], v[102:105], v[66:81]
	ds_read_b128 v[146:149], v220 offset:40064
	global_load_dwordx4 v[200:203], v226, s[4:5]
	global_load_dwordx4 v[204:207], v227, s[4:5]
	global_load_dwordx4 v[208:211], v228, s[4:5]
	s_add_u32 s4, s4, 0x6000
	s_addc_u32 s5, s5, 0
	global_load_dwordx4 v[212:215], v229, s[10:11]
	s_add_u32 s10, s10, 0x80
	s_addc_u32 s11, s11, 0
	v_exp_f32_e32 v41, v41
	v_add_f32_e32 v231, v231, v38
	v_add_f32_e32 v232, v232, v39
	v_mfma_f32_32x32x16_bf16 v[82:97], v[150:153], v[102:105], v[82:97]
	ds_read_b128 v[150:153], v220 offset:46720
	v_add_f32_e32 v231, v231, v40
	v_add_f32_e32 v232, v232, v41
	v_cvt_pk_bf16_f32 v34, v34, v35
	v_cvt_pk_bf16_f32 v35, v36, v37
	v_cvt_pk_bf16_f32 v36, v38, v39
	s_waitcnt lgkmcnt(4)
	v_mfma_f32_32x32x16_bf16 v[66:81], v[154:157], v[106:109], v[66:81]
	ds_read_b128 v[154:157], v220 offset:40096
	v_cvt_pk_bf16_f32 v37, v40, v41
	v_exp_f32_e32 v42, v42
	v_exp_f32_e32 v43, v43
	v_exp_f32_e32 v44, v44
	v_mfma_f32_32x32x16_bf16 v[82:97], v[158:161], v[106:109], v[82:97]
	ds_read_b128 v[158:161], v220 offset:46752
	v_exp_f32_e32 v45, v45
	v_add_f32_e32 v231, v231, v42
	v_add_f32_e32 v232, v232, v43
	s_waitcnt lgkmcnt(4)
	v_mfma_f32_32x32x16_bf16 v[66:81], v[138:141], v[110:113], v[66:81]
	ds_read_b128 v[162:165], v221 offset:18432
	v_exp_f32_e32 v46, v46
	v_exp_f32_e32 v47, v47
	v_add_f32_e32 v231, v231, v44
	v_add_f32_e32 v232, v232, v45
	v_mfma_f32_32x32x16_bf16 v[82:97], v[142:145], v[110:113], v[82:97]
	ds_read_b128 v[166:169], v221 offset:23040
	v_exp_f32_e32 v48, v48
	v_exp_f32_e32 v49, v49
	v_add_f32_e32 v231, v231, v46
	s_waitcnt lgkmcnt(4)
	v_mfma_f32_32x32x16_bf16 v[66:81], v[146:149], v[114:117], v[66:81]
	ds_read_b128 v[170:173], v221 offset:18464
	v_add_f32_e32 v232, v232, v47
	v_add_f32_e32 v231, v231, v48
	v_add_f32_e32 v232, v232, v49
	v_cvt_pk_bf16_f32 v42, v42, v43
	v_cvt_pk_bf16_f32 v43, v44, v45
	v_mfma_f32_32x32x16_bf16 v[82:97], v[150:153], v[114:117], v[82:97]
	ds_read_b128 v[174:177], v221 offset:23072
	v_cvt_pk_bf16_f32 v44, v46, v47
	v_cvt_pk_bf16_f32 v45, v48, v49
	v_exp_f32_e32 v50, v50
	v_exp_f32_e32 v51, v51
	s_waitcnt lgkmcnt(4)
	v_mfma_f32_32x32x16_bf16 v[66:81], v[154:157], v[118:121], v[66:81]
	ds_read_b128 v[180:183], v221 offset:18496
	v_exp_f32_e32 v52, v52
	v_exp_f32_e32 v53, v53
	v_add_f32_e32 v231, v231, v50
	v_mfma_f32_32x32x16_bf16 v[82:97], v[158:161], v[118:121], v[82:97]
	ds_read_b128 v[184:187], v221 offset:23104
	v_add_f32_e32 v232, v232, v51
	v_exp_f32_e32 v54, v54
	v_exp_f32_e32 v55, v55
	v_add_f32_e32 v231, v231, v52
	s_waitcnt lgkmcnt(4)
	v_mfma_f32_32x32x16_bf16 v[2:17], v[162:165], v[34:37], v[2:17]
	ds_read_b128 v[188:191], v221 offset:18528
	v_add_f32_e32 v232, v232, v53
	v_exp_f32_e32 v56, v56
	v_exp_f32_e32 v57, v57
	v_mfma_f32_32x32x16_bf16 v[18:33], v[166:169], v[34:37], v[18:33]
	ds_read_b128 v[192:195], v221 offset:23136
	v_add_f32_e32 v231, v231, v54
	v_add_f32_e32 v232, v232, v55
	v_add_f32_e32 v231, v231, v56
	v_add_f32_e32 v232, v232, v57
	v_cvt_pk_bf16_f32 v50, v50, v51
	s_waitcnt lgkmcnt(4)
	v_mfma_f32_32x32x16_bf16 v[2:17], v[170:173], v[42:45], v[2:17]
	v_cvt_pk_bf16_f32 v51, v52, v53
	v_cvt_pk_bf16_f32 v52, v54, v55
	v_cvt_pk_bf16_f32 v53, v56, v57
	v_exp_f32_e32 v58, v58
	v_mfma_f32_32x32x16_bf16 v[18:33], v[174:177], v[42:45], v[18:33]
	s_waitcnt vmcnt(4)
	ds_write_b64 v225, v[216:217] offset:0
	ds_write_b64 v225, v[218:219] offset:16
	v_exp_f32_e32 v59, v59
	v_exp_f32_e32 v60, v60
	v_exp_f32_e32 v61, v61
	s_waitcnt lgkmcnt(4)
	v_mfma_f32_32x32x16_bf16 v[2:17], v[180:183], v[50:53], v[2:17]
	v_add_f32_e32 v231, v231, v58
	v_add_f32_e32 v232, v232, v59
	v_exp_f32_e32 v62, v62
	v_exp_f32_e32 v63, v63
	v_mfma_f32_32x32x16_bf16 v[18:33], v[184:187], v[50:53], v[18:33]
	v_add_f32_e32 v231, v231, v60
	v_add_f32_e32 v232, v232, v61
	v_exp_f32_e32 v64, v64
	v_exp_f32_e32 v65, v65
	v_add_f32_e32 v231, v231, v62
	v_add_f32_e32 v232, v232, v63
	v_add_f32_e32 v231, v231, v64
	v_add_f32_e32 v232, v232, v65
	v_cvt_pk_bf16_f32 v58, v58, v59
	v_cvt_pk_bf16_f32 v59, v60, v61
	v_cvt_pk_bf16_f32 v60, v62, v63
	v_cvt_pk_bf16_f32 v61, v64, v65
	s_waitcnt lgkmcnt(2)
	s_nop 0
	v_mfma_f32_32x32x16_bf16 v[2:17], v[188:191], v[58:61], v[2:17]
	v_mfma_f32_32x32x16_bf16 v[18:33], v[192:195], v[58:61], v[18:33]
	ds_read_b128 v[138:141], v220 offset:0
	ds_read_b128 v[142:145], v220 offset:6656
	ds_read_b128 v[146:149], v220 offset:32
	ds_read_b128 v[150:153], v220 offset:6688
	ds_read_b128 v[154:157], v220 offset:64
	ds_read_b128 v[158:161], v220 offset:6720
	s_waitcnt lgkmcnt(6)
	s_barrier
	v_exp_f32_e32 v66, v66
	v_exp_f32_e32 v67, v67
	v_exp_f32_e32 v68, v68
	s_waitcnt lgkmcnt(4)
	v_mfma_f32_32x32x16_bf16 v[34:49], v[138:141], v[98:101], v[122:137]
	ds_read_b128 v[138:141], v220 offset:96
	v_exp_f32_e32 v69, v69
	v_add_f32_e32 v231, v231, v66
	v_add_f32_e32 v232, v232, v67
	v_exp_f32_e32 v70, v70
	v_mfma_f32_32x32x16_bf16 v[50:65], v[142:145], v[98:101], v[122:137]
	ds_read_b128 v[142:145], v220 offset:6752
	v_exp_f32_e32 v71, v71
	v_add_f32_e32 v231, v231, v68
	v_add_f32_e32 v232, v232, v69
	v_exp_f32_e32 v72, v72
	s_waitcnt lgkmcnt(4)
	v_mfma_f32_32x32x16_bf16 v[34:49], v[146:149], v[102:105], v[34:49]
	ds_read_b128 v[146:149], v220 offset:128
	global_load_dwordx4 v[216:219], v229, s[10:11]
	s_add_u32 s10, s10, 0x80
	s_addc_u32 s11, s11, 0
	v_exp_f32_e32 v73, v73
	v_add_f32_e32 v231, v231, v70
	v_add_f32_e32 v232, v232, v71
	v_mfma_f32_32x32x16_bf16 v[50:65], v[150:153], v[102:105], v[50:65]
	ds_read_b128 v[150:153], v220 offset:6784
	v_add_f32_e32 v231, v231, v72
	v_add_f32_e32 v232, v232, v73
	v_cvt_pk_bf16_f32 v66, v66, v67
	v_cvt_pk_bf16_f32 v67, v68, v69
	v_cvt_pk_bf16_f32 v68, v70, v71
	s_waitcnt lgkmcnt(4)
	v_mfma_f32_32x32x16_bf16 v[34:49], v[154:157], v[106:109], v[34:49]
	ds_read_b128 v[154:157], v220 offset:160
	v_cvt_pk_bf16_f32 v69, v72, v73
	v_exp_f32_e32 v74, v74
	v_exp_f32_e32 v75, v75
	v_exp_f32_e32 v76, v76
	v_mfma_f32_32x32x16_bf16 v[50:65], v[158:161], v[106:109], v[50:65]
	ds_read_b128 v[158:161], v220 offset:6816
	v_exp_f32_e32 v77, v77
	v_add_f32_e32 v231, v231, v74
	v_add_f32_e32 v232, v232, v75
	s_waitcnt lgkmcnt(4)
	v_mfma_f32_32x32x16_bf16 v[34:49], v[138:141], v[110:113], v[34:49]
	ds_read_b128 v[162:165], v221 offset:27648
	v_exp_f32_e32 v78, v78
	v_exp_f32_e32 v79, v79
	v_add_f32_e32 v231, v231, v76
	v_add_f32_e32 v232, v232, v77
	v_mfma_f32_32x32x16_bf16 v[50:65], v[142:145], v[110:113], v[50:65]
	ds_read_b128 v[166:169], v221 offset:32256
	v_exp_f32_e32 v80, v80
	v_exp_f32_e32 v81, v81
	v_add_f32_e32 v231, v231, v78
	s_waitcnt lgkmcnt(4)
	v_mfma_f32_32x32x16_bf16 v[34:49], v[146:149], v[114:117], v[34:49]
	ds_read_b128 v[170:173], v221 offset:27680
	v_add_f32_e32 v232, v232, v79
	v_add_f32_e32 v231, v231, v80
	v_add_f32_e32 v232, v232, v81
	v_cvt_pk_bf16_f32 v74, v74, v75
	v_cvt_pk_bf16_f32 v75, v76, v77
	v_mfma_f32_32x32x16_bf16 v[50:65], v[150:153], v[114:117], v[50:65]
	ds_read_b128 v[174:177], v221 offset:32288
	v_cvt_pk_bf16_f32 v76, v78, v79
	v_cvt_pk_bf16_f32 v77, v80, v81
	v_exp_f32_e32 v82, v82
	v_exp_f32_e32 v83, v83
	s_waitcnt lgkmcnt(4)
	v_mfma_f32_32x32x16_bf16 v[34:49], v[154:157], v[118:121], v[34:49]
	ds_read_b128 v[180:183], v221 offset:27712
	v_exp_f32_e32 v84, v84
	v_exp_f32_e32 v85, v85
	v_add_f32_e32 v231, v231, v82
	v_mfma_f32_32x32x16_bf16 v[50:65], v[158:161], v[118:121], v[50:65]
	ds_read_b128 v[184:187], v221 offset:32320
	v_add_f32_e32 v232, v232, v83
	v_exp_f32_e32 v86, v86
	v_exp_f32_e32 v87, v87
	v_add_f32_e32 v231, v231, v84
	s_waitcnt lgkmcnt(4)
	v_mfma_f32_32x32x16_bf16 v[2:17], v[162:165], v[66:69], v[2:17]
	ds_read_b128 v[188:191], v221 offset:27744
	v_add_f32_e32 v232, v232, v85
	v_exp_f32_e32 v88, v88
	v_exp_f32_e32 v89, v89
	v_mfma_f32_32x32x16_bf16 v[18:33], v[166:169], v[66:69], v[18:33]
	ds_read_b128 v[192:195], v221 offset:32352
	v_add_f32_e32 v231, v231, v86
	v_add_f32_e32 v232, v232, v87
	v_add_f32_e32 v231, v231, v88
	v_add_f32_e32 v232, v232, v89
	v_cvt_pk_bf16_f32 v82, v82, v83
	s_waitcnt lgkmcnt(4)
	v_mfma_f32_32x32x16_bf16 v[2:17], v[170:173], v[74:77], v[2:17]
	v_cvt_pk_bf16_f32 v83, v84, v85
	v_cvt_pk_bf16_f32 v84, v86, v87
	v_cvt_pk_bf16_f32 v85, v88, v89
	v_exp_f32_e32 v90, v90
	v_mfma_f32_32x32x16_bf16 v[18:33], v[174:177], v[74:77], v[18:33]
	s_waitcnt vmcnt(1)
	ds_write_b128 v222, v[200:203] offset:26624
	ds_write_b128 v223, v[204:207] offset:26624
	ds_write_b128 v224, v[208:211] offset:26624
	ds_write_b64 v225, v[212:213] offset:9216
	ds_write_b64 v225, v[214:215] offset:9232
	v_exp_f32_e32 v91, v91
	v_exp_f32_e32 v92, v92
	v_exp_f32_e32 v93, v93
	s_waitcnt lgkmcnt(7)
	v_mfma_f32_32x32x16_bf16 v[2:17], v[180:183], v[82:85], v[2:17]
	v_add_f32_e32 v231, v231, v90
	v_add_f32_e32 v232, v232, v91
	v_exp_f32_e32 v94, v94
	v_exp_f32_e32 v95, v95
	v_mfma_f32_32x32x16_bf16 v[18:33], v[184:187], v[82:85], v[18:33]
	v_add_f32_e32 v231, v231, v92
	v_add_f32_e32 v232, v232, v93
	v_exp_f32_e32 v96, v96
	v_exp_f32_e32 v97, v97
	v_add_f32_e32 v231, v231, v94
	v_add_f32_e32 v232, v232, v95
	v_add_f32_e32 v231, v231, v96
	v_add_f32_e32 v232, v232, v97
	v_cvt_pk_bf16_f32 v90, v90, v91
	v_cvt_pk_bf16_f32 v91, v92, v93
	v_cvt_pk_bf16_f32 v92, v94, v95
	v_cvt_pk_bf16_f32 v93, v96, v97
	s_waitcnt lgkmcnt(5)
	s_nop 0
	v_mfma_f32_32x32x16_bf16 v[2:17], v[188:191], v[90:93], v[2:17]
	v_mfma_f32_32x32x16_bf16 v[18:33], v[192:195], v[90:93], v[18:33]
	ds_read_b128 v[138:141], v220 offset:13312
	ds_read_b128 v[142:145], v220 offset:19968
	ds_read_b128 v[146:149], v220 offset:13344
	ds_read_b128 v[150:153], v220 offset:20000
	ds_read_b128 v[154:157], v220 offset:13376
	ds_read_b128 v[158:161], v220 offset:20032
	s_waitcnt lgkmcnt(6)
	s_barrier
	s_add_i32 s16, s16, -1
	s_cmp_lg_u32 s16, 0
	s_cbranch_scc1 .Lmla_loop
	v_exp_f32_e32 v34, v34
	v_exp_f32_e32 v35, v35
	v_exp_f32_e32 v36, v36
	s_waitcnt lgkmcnt(4)
	v_mfma_f32_32x32x16_bf16 v[66:81], v[138:141], v[98:101], v[122:137]
	ds_read_b128 v[138:141], v220 offset:13408
	v_exp_f32_e32 v37, v37
	v_add_f32_e32 v231, v231, v34
	v_add_f32_e32 v232, v232, v35
	v_exp_f32_e32 v38, v38
	v_mfma_f32_32x32x16_bf16 v[82:97], v[142:145], v[98:101], v[122:137]
	ds_read_b128 v[142:145], v220 offset:20064
	v_exp_f32_e32 v39, v39
	v_add_f32_e32 v231, v231, v36
	v_add_f32_e32 v232, v232, v37
	v_exp_f32_e32 v40, v40
	s_waitcnt lgkmcnt(4)
	v_mfma_f32_32x32x16_bf16 v[66:81], v[146:149], v[102:105], v[66:81]
	ds_read_b128 v[146:149], v220 offset:13440
	global_load_dwordx4 v[212:215], v229, s[10:11]
	s_add_u32 s10, s10, 0x80
	s_addc_u32 s11, s11, 0
	v_exp_f32_e32 v41, v41
	v_add_f32_e32 v231, v231, v38
	v_add_f32_e32 v232, v232, v39
	v_mfma_f32_32x32x16_bf16 v[82:97], v[150:153], v[102:105], v[82:97]
	ds_read_b128 v[150:153], v220 offset:20096
	v_add_f32_e32 v231, v231, v40
	v_add_f32_e32 v232, v232, v41
	v_cvt_pk_bf16_f32 v34, v34, v35
	v_cvt_pk_bf16_f32 v35, v36, v37
	v_cvt_pk_bf16_f32 v36, v38, v39
	s_waitcnt lgkmcnt(4)
	v_mfma_f32_32x32x16_bf16 v[66:81], v[154:157], v[106:109], v[66:81]
	ds_read_b128 v[154:157], v220 offset:13472
	v_cvt_pk_bf16_f32 v37, v40, v41
	v_exp_f32_e32 v42, v42
	v_exp_f32_e32 v43, v43
	v_exp_f32_e32 v44, v44
	v_mfma_f32_32x32x16_bf16 v[82:97], v[158:161], v[106:109], v[82:97]
	ds_read_b128 v[158:161], v220 offset:20128
	v_exp_f32_e32 v45, v45
	v_add_f32_e32 v231, v231, v42
	v_add_f32_e32 v232, v232, v43
	s_waitcnt lgkmcnt(4)
	v_mfma_f32_32x32x16_bf16 v[66:81], v[138:141], v[110:113], v[66:81]
	ds_read_b128 v[162:165], v221 offset:0
	v_exp_f32_e32 v46, v46
	v_exp_f32_e32 v47, v47
	v_add_f32_e32 v231, v231, v44
	v_add_f32_e32 v232, v232, v45
	v_mfma_f32_32x32x16_bf16 v[82:97], v[142:145], v[110:113], v[82:97]
	ds_read_b128 v[166:169], v221 offset:4608
	v_exp_f32_e32 v48, v48
	v_exp_f32_e32 v49, v49
	v_add_f32_e32 v231, v231, v46
	s_waitcnt lgkmcnt(4)
	v_mfma_f32_32x32x16_bf16 v[66:81], v[146:149], v[114:117], v[66:81]
	ds_read_b128 v[170:173], v221 offset:32
	v_add_f32_e32 v232, v232, v47
	v_add_f32_e32 v231, v231, v48
	v_add_f32_e32 v232, v232, v49
	v_cvt_pk_bf16_f32 v42, v42, v43
	v_cvt_pk_bf16_f32 v43, v44, v45
	v_mfma_f32_32x32x16_bf16 v[82:97], v[150:153], v[114:117], v[82:97]
	ds_read_b128 v[174:177], v221 offset:4640
	v_cvt_pk_bf16_f32 v44, v46, v47
	v_cvt_pk_bf16_f32 v45, v48, v49
	v_exp_f32_e32 v50, v50
	v_exp_f32_e32 v51, v51
	s_waitcnt lgkmcnt(4)
	v_mfma_f32_32x32x16_bf16 v[66:81], v[154:157], v[118:121], v[66:81]
	ds_read_b128 v[180:183], v221 offset:64
	v_exp_f32_e32 v52, v52
	v_exp_f32_e32 v53, v53
	v_add_f32_e32 v231, v231, v50
	v_mfma_f32_32x32x16_bf16 v[82:97], v[158:161], v[118:121], v[82:97]
	ds_read_b128 v[184:187], v221 offset:4672
	v_add_f32_e32 v232, v232, v51
	v_exp_f32_e32 v54, v54
	v_exp_f32_e32 v55, v55
	v_add_f32_e32 v231, v231, v52
	s_waitcnt lgkmcnt(4)
	v_mfma_f32_32x32x16_bf16 v[2:17], v[162:165], v[34:37], v[2:17]
	ds_read_b128 v[188:191], v221 offset:96
	v_add_f32_e32 v232, v232, v53
	v_exp_f32_e32 v56, v56
	v_exp_f32_e32 v57, v57
	v_mfma_f32_32x32x16_bf16 v[18:33], v[166:169], v[34:37], v[18:33]
	ds_read_b128 v[192:195], v221 offset:4704
	v_add_f32_e32 v231, v231, v54
	v_add_f32_e32 v232, v232, v55
	v_add_f32_e32 v231, v231, v56
	v_add_f32_e32 v232, v232, v57
	v_cvt_pk_bf16_f32 v50, v50, v51
	s_waitcnt lgkmcnt(4)
	v_mfma_f32_32x32x16_bf16 v[2:17], v[170:173], v[42:45], v[2:17]
	v_cvt_pk_bf16_f32 v51, v52, v53
	v_cvt_pk_bf16_f32 v52, v54, v55
	v_cvt_pk_bf16_f32 v53, v56, v57
	v_exp_f32_e32 v58, v58
	v_mfma_f32_32x32x16_bf16 v[18:33], v[174:177], v[42:45], v[18:33]
	s_waitcnt vmcnt(1)
	ds_write_b64 v225, v[216:217] offset:18432
	ds_write_b64 v225, v[218:219] offset:18448
	v_exp_f32_e32 v59, v59
	v_exp_f32_e32 v60, v60
	v_exp_f32_e32 v61, v61
	s_waitcnt lgkmcnt(4)
	v_mfma_f32_32x32x16_bf16 v[2:17], v[180:183], v[50:53], v[2:17]
	v_add_f32_e32 v231, v231, v58
	v_add_f32_e32 v232, v232, v59
	v_exp_f32_e32 v62, v62
	v_exp_f32_e32 v63, v63
	v_mfma_f32_32x32x16_bf16 v[18:33], v[184:187], v[50:53], v[18:33]
	v_add_f32_e32 v231, v231, v60
	v_add_f32_e32 v232, v232, v61
	v_exp_f32_e32 v64, v64
	v_exp_f32_e32 v65, v65
	v_add_f32_e32 v231, v231, v62
	v_add_f32_e32 v232, v232, v63
	v_add_f32_e32 v231, v231, v64
	v_add_f32_e32 v232, v232, v65
	v_cvt_pk_bf16_f32 v58, v58, v59
	v_cvt_pk_bf16_f32 v59, v60, v61
	v_cvt_pk_bf16_f32 v60, v62, v63
	v_cvt_pk_bf16_f32 v61, v64, v65
	s_waitcnt lgkmcnt(2)
	s_nop 0
	v_mfma_f32_32x32x16_bf16 v[2:17], v[188:191], v[58:61], v[2:17]
	v_mfma_f32_32x32x16_bf16 v[18:33], v[192:195], v[58:61], v[18:33]
	ds_read_b128 v[138:141], v220 offset:26624
	ds_read_b128 v[142:145], v220 offset:33280
	ds_read_b128 v[146:149], v220 offset:26656
	ds_read_b128 v[150:153], v220 offset:33312
	ds_read_b128 v[154:157], v220 offset:26688
	ds_read_b128 v[158:161], v220 offset:33344
	s_waitcnt lgkmcnt(6)
	s_barrier
	v_exp_f32_e32 v66, v66
	v_exp_f32_e32 v67, v67
	v_exp_f32_e32 v68, v68
	s_waitcnt lgkmcnt(4)
	v_mfma_f32_32x32x16_bf16 v[34:49], v[138:141], v[98:101], v[122:137]
	ds_read_b128 v[138:141], v220 offset:26720
	v_exp_f32_e32 v69, v69
	v_add_f32_e32 v231, v231, v66
	v_add_f32_e32 v232, v232, v67
	v_exp_f32_e32 v70, v70
	v_mfma_f32_32x32x16_bf16 v[50:65], v[142:145], v[98:101], v[122:137]
	ds_read_b128 v[142:145], v220 offset:33376
	v_exp_f32_e32 v71, v71
	v_add_f32_e32 v231, v231, v68
	v_add_f32_e32 v232, v232, v69
	v_exp_f32_e32 v72, v72
	s_waitcnt lgkmcnt(4)
	v_mfma_f32_32x32x16_bf16 v[34:49], v[146:149], v[102:105], v[34:49]
	ds_read_b128 v[146:149], v220 offset:26752
	v_exp_f32_e32 v73, v73
	v_add_f32_e32 v231, v231, v70
	v_add_f32_e32 v232, v232, v71
	v_mfma_f32_32x32x16_bf16 v[50:65], v[150:153], v[102:105], v[50:65]
	ds_read_b128 v[150:153], v220 offset:33408
	v_add_f32_e32 v231, v231, v72
	v_add_f32_e32 v232, v232, v73
	v_cvt_pk_bf16_f32 v66, v66, v67
	v_cvt_pk_bf16_f32 v67, v68, v69
	v_cvt_pk_bf16_f32 v68, v70, v71
	s_waitcnt lgkmcnt(4)
	v_mfma_f32_32x32x16_bf16 v[34:49], v[154:157], v[106:109], v[34:49]
	ds_read_b128 v[154:157], v220 offset:26784
	v_cvt_pk_bf16_f32 v69, v72, v73
	v_exp_f32_e32 v74, v74
	v_exp_f32_e32 v75, v75
	v_exp_f32_e32 v76, v76
	v_mfma_f32_32x32x16_bf16 v[50:65], v[158:161], v[106:109], v[50:65]
	ds_read_b128 v[158:161], v220 offset:33440
	v_exp_f32_e32 v77, v77
	v_add_f32_e32 v231, v231, v74
	v_add_f32_e32 v232, v232, v75
	s_waitcnt lgkmcnt(4)
	v_mfma_f32_32x32x16_bf16 v[34:49], v[138:141], v[110:113], v[34:49]
	ds_read_b128 v[162:165], v221 offset:9216
	v_exp_f32_e32 v78, v78
	v_exp_f32_e32 v79, v79
	v_add_f32_e32 v231, v231, v76
	v_add_f32_e32 v232, v232, v77
	v_mfma_f32_32x32x16_bf16 v[50:65], v[142:145], v[110:113], v[50:65]
	ds_read_b128 v[166:169], v221 offset:13824
	v_exp_f32_e32 v80, v80
	v_exp_f32_e32 v81, v81
	v_add_f32_e32 v231, v231, v78
	s_waitcnt lgkmcnt(4)
	v_mfma_f32_32x32x16_bf16 v[34:49], v[146:149], v[114:117], v[34:49]
	ds_read_b128 v[170:173], v221 offset:9248
	v_add_f32_e32 v232, v232, v79
	v_add_f32_e32 v231, v231, v80
	v_add_f32_e32 v232, v232, v81
	v_cvt_pk_bf16_f32 v74, v74, v75
	v_cvt_pk_bf16_f32 v75, v76, v77
	v_mfma_f32_32x32x16_bf16 v[50:65], v[150:153], v[114:117], v[50:65]
	ds_read_b128 v[174:177], v221 offset:13856
	v_cvt_pk_bf16_f32 v76, v78, v79
	v_cvt_pk_bf16_f32 v77, v80, v81
	v_exp_f32_e32 v82, v82
	v_exp_f32_e32 v83, v83
	s_waitcnt lgkmcnt(4)
	v_mfma_f32_32x32x16_bf16 v[34:49], v[154:157], v[118:121], v[34:49]
	ds_read_b128 v[180:183], v221 offset:9280
	v_exp_f32_e32 v84, v84
	v_exp_f32_e32 v85, v85
	v_add_f32_e32 v231, v231, v82
	v_mfma_f32_32x32x16_bf16 v[50:65], v[158:161], v[118:121], v[50:65]
	ds_read_b128 v[184:187], v221 offset:13888
	v_add_f32_e32 v232, v232, v83
	v_exp_f32_e32 v86, v86
	v_exp_f32_e32 v87, v87
	v_add_f32_e32 v231, v231, v84
	s_waitcnt lgkmcnt(4)
	v_mfma_f32_32x32x16_bf16 v[2:17], v[162:165], v[66:69], v[2:17]
	ds_read_b128 v[188:191], v221 offset:9312
	v_add_f32_e32 v232, v232, v85
	v_exp_f32_e32 v88, v88
	v_exp_f32_e32 v89, v89
	v_mfma_f32_32x32x16_bf16 v[18:33], v[166:169], v[66:69], v[18:33]
	ds_read_b128 v[192:195], v221 offset:13920
	v_add_f32_e32 v231, v231, v86
	v_add_f32_e32 v232, v232, v87
	v_add_f32_e32 v231, v231, v88
	v_add_f32_e32 v232, v232, v89
	v_cvt_pk_bf16_f32 v82, v82, v83
	s_waitcnt lgkmcnt(4)
	v_mfma_f32_32x32x16_bf16 v[2:17], v[170:173], v[74:77], v[2:17]
	v_cvt_pk_bf16_f32 v83, v84, v85
	v_cvt_pk_bf16_f32 v84, v86, v87
	v_cvt_pk_bf16_f32 v85, v88, v89
	v_exp_f32_e32 v90, v90
	v_mfma_f32_32x32x16_bf16 v[18:33], v[174:177], v[74:77], v[18:33]
	s_waitcnt vmcnt(0)
	ds_write_b64 v225, v[212:213] offset:27648
	ds_write_b64 v225, v[214:215] offset:27664
	v_exp_f32_e32 v91, v91
	v_exp_f32_e32 v92, v92
	v_exp_f32_e32 v93, v93
	s_waitcnt lgkmcnt(4)
	v_mfma_f32_32x32x16_bf16 v[2:17], v[180:183], v[82:85], v[2:17]
	v_add_f32_e32 v231, v231, v90
	v_add_f32_e32 v232, v232, v91
	v_exp_f32_e32 v94, v94
	v_exp_f32_e32 v95, v95
	v_mfma_f32_32x32x16_bf16 v[18:33], v[184:187], v[82:85], v[18:33]
	v_add_f32_e32 v231, v231, v92
	v_add_f32_e32 v232, v232, v93
	v_exp_f32_e32 v96, v96
	v_exp_f32_e32 v97, v97
	v_add_f32_e32 v231, v231, v94
	v_add_f32_e32 v232, v232, v95
	v_add_f32_e32 v231, v231, v96
	v_add_f32_e32 v232, v232, v97
	v_cvt_pk_bf16_f32 v90, v90, v91
	v_cvt_pk_bf16_f32 v91, v92, v93
	v_cvt_pk_bf16_f32 v92, v94, v95
	v_cvt_pk_bf16_f32 v93, v96, v97
	s_waitcnt lgkmcnt(2)
	s_nop 0
	v_mfma_f32_32x32x16_bf16 v[2:17], v[188:191], v[90:93], v[2:17]
	v_mfma_f32_32x32x16_bf16 v[18:33], v[192:195], v[90:93], v[18:33]
	ds_read_b128 v[138:141], v220 offset:39936
	ds_read_b128 v[142:145], v220 offset:46592
	ds_read_b128 v[146:149], v220 offset:39968
	ds_read_b128 v[150:153], v220 offset:46624
	ds_read_b128 v[154:157], v220 offset:40000
	ds_read_b128 v[158:161], v220 offset:46656
	s_waitcnt lgkmcnt(6)
	s_barrier
	global_load_dwordx2 v[200:201], v236, s[14:15] offset:0
	global_load_dwordx2 v[202:203], v236, s[14:15] offset:16
	global_load_dwordx2 v[204:205], v236, s[14:15] offset:32
	global_load_dwordx2 v[206:207], v236, s[14:15] offset:48
	global_load_dwordx2 v[208:209], v236, s[14:15] offset:64
	global_load_dwordx2 v[210:211], v236, s[14:15] offset:80
	global_load_dwordx2 v[212:213], v236, s[14:15] offset:96
	global_load_dwordx2 v[214:215], v236, s[14:15] offset:112
	v_exp_f32_e32 v34, v34
	v_exp_f32_e32 v35, v35
	v_exp_f32_e32 v36, v36
	s_waitcnt lgkmcnt(4)
	v_mfma_f32_32x32x16_bf16 v[66:81], v[138:141], v[98:101], v[122:137]
	ds_read_b128 v[138:141], v220 offset:40032
	v_exp_f32_e32 v37, v37
	v_add_f32_e32 v231, v231, v34
	v_add_f32_e32 v232, v232, v35
	v_exp_f32_e32 v38, v38
	v_mfma_f32_32x32x16_bf16 v[82:97], v[142:145], v[98:101], v[122:137]
	ds_read_b128 v[142:145], v220 offset:46688
	v_exp_f32_e32 v39, v39
	v_add_f32_e32 v231, v231, v36
	v_add_f32_e32 v232, v232, v37
	v_exp_f32_e32 v40, v40
	s_waitcnt lgkmcnt(4)
	v_mfma_f32_32x32x16_bf16 v[66:81], v[146:149], v[102:105], v[66:81]
	ds_read_b128 v[146:149], v220 offset:40064
	v_exp_f32_e32 v41, v41
	v_add_f32_e32 v231, v231, v38
	v_add_f32_e32 v232, v232, v39
	v_mfma_f32_32x32x16_bf16 v[82:97], v[150:153], v[102:105], v[82:97]
	ds_read_b128 v[150:153], v220 offset:46720
	v_add_f32_e32 v231, v231, v40
	v_add_f32_e32 v232, v232, v41
	v_cvt_pk_bf16_f32 v34, v34, v35
	v_cvt_pk_bf16_f32 v35, v36, v37
	v_cvt_pk_bf16_f32 v36, v38, v39
	s_waitcnt lgkmcnt(4)
	v_mfma_f32_32x32x16_bf16 v[66:81], v[154:157], v[106:109], v[66:81]
	ds_read_b128 v[154:157], v220 offset:40096
	v_cvt_pk_bf16_f32 v37, v40, v41
	v_exp_f32_e32 v42, v42
	v_exp_f32_e32 v43, v43
	v_exp_f32_e32 v44, v44
	v_mfma_f32_32x32x16_bf16 v[82:97], v[158:161], v[106:109], v[82:97]
	ds_read_b128 v[158:161], v220 offset:46752
	v_exp_f32_e32 v45, v45
	v_add_f32_e32 v231, v231, v42
	v_add_f32_e32 v232, v232, v43
	s_waitcnt lgkmcnt(4)
	v_mfma_f32_32x32x16_bf16 v[66:81], v[138:141], v[110:113], v[66:81]
	ds_read_b128 v[162:165], v221 offset:18432
	v_exp_f32_e32 v46, v46
	v_exp_f32_e32 v47, v47
	v_add_f32_e32 v231, v231, v44
	v_add_f32_e32 v232, v232, v45
	v_mfma_f32_32x32x16_bf16 v[82:97], v[142:145], v[110:113], v[82:97]
	ds_read_b128 v[166:169], v221 offset:23040
	v_exp_f32_e32 v48, v48
	v_exp_f32_e32 v49, v49
	v_add_f32_e32 v231, v231, v46
	s_waitcnt lgkmcnt(4)
	v_mfma_f32_32x32x16_bf16 v[66:81], v[146:149], v[114:117], v[66:81]
	ds_read_b128 v[170:173], v221 offset:18464
	v_add_f32_e32 v232, v232, v47
	v_add_f32_e32 v231, v231, v48
	v_add_f32_e32 v232, v232, v49
	v_cvt_pk_bf16_f32 v42, v42, v43
	v_cvt_pk_bf16_f32 v43, v44, v45
	v_mfma_f32_32x32x16_bf16 v[82:97], v[150:153], v[114:117], v[82:97]
	ds_read_b128 v[174:177], v221 offset:23072
	v_cvt_pk_bf16_f32 v44, v46, v47
	v_cvt_pk_bf16_f32 v45, v48, v49
	v_exp_f32_e32 v50, v50
	v_exp_f32_e32 v51, v51
	s_waitcnt lgkmcnt(4)
	v_mfma_f32_32x32x16_bf16 v[66:81], v[154:157], v[118:121], v[66:81]
	ds_read_b128 v[180:183], v221 offset:18496
	v_exp_f32_e32 v52, v52
	v_exp_f32_e32 v53, v53
	v_add_f32_e32 v231, v231, v50
	v_mfma_f32_32x32x16_bf16 v[82:97], v[158:161], v[118:121], v[82:97]
	ds_read_b128 v[184:187], v221 offset:23104
	v_add_f32_e32 v232, v232, v51
	v_exp_f32_e32 v54, v54
	v_exp_f32_e32 v55, v55
	v_add_f32_e32 v231, v231, v52
	s_waitcnt lgkmcnt(4)
	v_mfma_f32_32x32x16_bf16 v[2:17], v[162:165], v[34:37], v[2:17]
	ds_read_b128 v[188:191], v221 offset:18528
	v_add_f32_e32 v232, v232, v53
	v_exp_f32_e32 v56, v56
	v_exp_f32_e32 v57, v57
	v_mfma_f32_32x32x16_bf16 v[18:33], v[166:169], v[34:37], v[18:33]
	ds_read_b128 v[192:195], v221 offset:23136
	v_add_f32_e32 v231, v231, v54
	v_add_f32_e32 v232, v232, v55
	v_add_f32_e32 v231, v231, v56
	v_add_f32_e32 v232, v232, v57
	v_cvt_pk_bf16_f32 v50, v50, v51
	s_waitcnt lgkmcnt(4)
	v_mfma_f32_32x32x16_bf16 v[2:17], v[170:173], v[42:45], v[2:17]
	v_cvt_pk_bf16_f32 v51, v52, v53
	v_cvt_pk_bf16_f32 v52, v54, v55
	v_cvt_pk_bf16_f32 v53, v56, v57
	v_exp_f32_e32 v58, v58
	v_mfma_f32_32x32x16_bf16 v[18:33], v[174:177], v[42:45], v[18:33]
	v_exp_f32_e32 v59, v59
	v_exp_f32_e32 v60, v60
	v_exp_f32_e32 v61, v61
	s_waitcnt lgkmcnt(2)
	v_mfma_f32_32x32x16_bf16 v[2:17], v[180:183], v[50:53], v[2:17]
	v_add_f32_e32 v231, v231, v58
	v_add_f32_e32 v232, v232, v59
	v_exp_f32_e32 v62, v62
	v_exp_f32_e32 v63, v63
	v_mfma_f32_32x32x16_bf16 v[18:33], v[184:187], v[50:53], v[18:33]
	v_add_f32_e32 v231, v231, v60
	v_add_f32_e32 v232, v232, v61
	v_exp_f32_e32 v64, v64
	v_exp_f32_e32 v65, v65
	v_add_f32_e32 v231, v231, v62
	v_add_f32_e32 v232, v232, v63
	v_add_f32_e32 v231, v231, v64
	v_add_f32_e32 v232, v232, v65
	v_cvt_pk_bf16_f32 v58, v58, v59
	v_cvt_pk_bf16_f32 v59, v60, v61
	v_cvt_pk_bf16_f32 v60, v62, v63
	v_cvt_pk_bf16_f32 v61, v64, v65
	s_waitcnt lgkmcnt(0)
	s_nop 0
	v_mfma_f32_32x32x16_bf16 v[2:17], v[188:191], v[58:61], v[2:17]
	v_mfma_f32_32x32x16_bf16 v[18:33], v[192:195], v[58:61], v[18:33]
	s_waitcnt lgkmcnt(0)
	s_barrier
	s_mov_b64 s[24:25], s[14:15]
	s_add_i32 s2, s2, s88
	s_cmpk_lt_i32 s2, 0x200
	s_cbranch_scc0 .Lmla_nopf
	s_lshr_b32 s17, s2, 4
	s_and_b32 s18, s2, 15
	s_mul_i32 s19, s17, 0xcc000
	s_add_u32 s4, s78, s19
	s_addc_u32 s5, s79, 0
	s_mul_i32 s19, s17, 0x88000
	s_add_u32 s19, s19, 0x1a00000
	s_add_u32 s10, s78, s19
	s_addc_u32 s11, s79, 0
	s_lshl_b32 s19, s17, 12
	s_lshl_b32 s20, s18, 8
	s_add_u32 s19, s19, s20
	s_mul_i32 s19, s19, 0xc0
	s_add_u32 s19, s19, 0x1400000
	s_add_u32 s12, s80, s19
	s_addc_u32 s13, s81, 0
	s_lshr_b32 s19, s17, 3
	s_lshl_b32 s19, s19, 12
	s_add_u32 s19, s19, s20
	s_lshl_b32 s19, s19, 10
	s_and_b32 s21, s17, 7
	s_lshl_b32 s21, s21, 7
	s_add_u32 s19, s19, s21
	s_add_u32 s19, s19, 0x7900000
	s_add_u32 s14, s80, s19
	s_addc_u32 s15, s81, 0
	global_load_dwordx4 v[98:101], v237, s[12:13] offset:0
	global_load_dwordx4 v[102:105], v237, s[12:13] offset:32
	global_load_dwordx4 v[106:109], v237, s[12:13] offset:64
	global_load_dwordx4 v[110:113], v237, s[12:13] offset:96
	global_load_dwordx4 v[114:117], v237, s[12:13] offset:128
	global_load_dwordx4 v[118:121], v237, s[12:13] offset:160
	global_load_dwordx4 v[34:37], v226, s[4:5]
	global_load_dwordx4 v[38:41], v227, s[4:5]
	global_load_dwordx4 v[42:45], v228, s[4:5]
	global_load_dwordx4 v[46:49], v229, s[10:11]
	s_add_u32 s4, s4, 0x6000
	s_addc_u32 s5, s5, 0
	global_load_dwordx4 v[50:53], v226, s[4:5]
	global_load_dwordx4 v[54:57], v227, s[4:5]
	global_load_dwordx4 v[58:61], v228, s[4:5]
	global_load_dwordx4 v[62:65], v229, s[10:11] offset:128
	global_load_dwordx4 v[216:219], v229, s[10:11] offset:256
	s_add_u32 s4, s4, 0x6000
	s_addc_u32 s5, s5, 0
	s_add_u32 s10, s10, 0x180
	s_addc_u32 s11, s11, 0

.Lmls_loop:
	v_exp_f32_e32 v34, v34
	v_exp_f32_e32 v35, v35
	v_exp_f32_e32 v36, v36
	v_exp_f32_e32 v37, v37
	s_waitcnt lgkmcnt(4)
	v_mfma_f32_32x32x16_bf16 v[66:81], v[138:141], v[98:101], v[122:137]
	ds_read_b128 v[138:141], v220 offset:13408
	v_add_f32_e32 v231, v231, v34
	v_add_f32_e32 v232, v232, v35
	v_exp_f32_e32 v38, v38
	v_exp_f32_e32 v39, v39
	v_mfma_f32_32x32x16_bf16 v[82:97], v[142:145], v[98:101], v[122:137]
	ds_read_b128 v[142:145], v220 offset:20064
	v_add_f32_e32 v231, v231, v36
	v_add_f32_e32 v232, v232, v37
	v_exp_f32_e32 v40, v40
	v_exp_f32_e32 v41, v41
	v_add_f32_e32 v231, v231, v38
	s_waitcnt lgkmcnt(4)
	v_mfma_f32_32x32x16_bf16 v[66:81], v[146:149], v[102:105], v[66:81]
	ds_read_b128 v[146:149], v220 offset:13440
	global_load_dwordx4 v[200:203], v226, s[4:5]
	global_load_dwordx4 v[204:207], v227, s[4:5]
	global_load_dwordx4 v[208:211], v228, s[4:5]
	s_add_u32 s4, s4, 0x6000
	s_addc_u32 s5, s5, 0
	global_load_dwordx4 v[212:215], v229, s[10:11]
	s_add_u32 s10, s10, 0x80
	s_addc_u32 s11, s11, 0
	v_add_f32_e32 v232, v232, v39
	v_add_f32_e32 v231, v231, v40
	v_add_f32_e32 v232, v232, v41
	v_cvt_pk_bf16_f32 v34, v34, v35
	v_cvt_pk_bf16_f32 v35, v36, v37
	v_mfma_f32_32x32x16_bf16 v[82:97], v[150:153], v[102:105], v[82:97]
	ds_read_b128 v[150:153], v220 offset:20096
	v_cvt_pk_bf16_f32 v36, v38, v39
	v_cvt_pk_bf16_f32 v37, v40, v41
	v_exp_f32_e32 v42, v42
	v_exp_f32_e32 v43, v43
	v_exp_f32_e32 v44, v44
	s_waitcnt lgkmcnt(4)
	v_mfma_f32_32x32x16_bf16 v[66:81], v[154:157], v[106:109], v[66:81]
	ds_read_b128 v[154:157], v220 offset:13472
	v_exp_f32_e32 v45, v45
	v_add_f32_e32 v231, v231, v42
	v_add_f32_e32 v232, v232, v43
	v_exp_f32_e32 v46, v46
	v_mfma_f32_32x32x16_bf16 v[82:97], v[158:161], v[106:109], v[82:97]
	ds_read_b128 v[158:161], v220 offset:20128
	v_exp_f32_e32 v47, v47
	v_add_f32_e32 v231, v231, v44
	v_add_f32_e32 v232, v232, v45
	v_exp_f32_e32 v48, v48
	s_waitcnt lgkmcnt(4)
	v_mfma_f32_32x32x16_bf16 v[66:81], v[138:141], v[110:113], v[66:81]
	ds_read_b128 v[162:165], v221 offset:0
	v_exp_f32_e32 v49, v49
	v_add_f32_e32 v231, v231, v46
	v_add_f32_e32 v232, v232, v47
	v_add_f32_e32 v231, v231, v48
	v_add_f32_e32 v232, v232, v49
	v_mfma_f32_32x32x16_bf16 v[82:97], v[142:145], v[110:113], v[82:97]
	ds_read_b128 v[166:169], v221 offset:4608
	v_cvt_pk_bf16_f32 v42, v42, v43
	v_cvt_pk_bf16_f32 v43, v44, v45
	v_cvt_pk_bf16_f32 v44, v46, v47
	v_cvt_pk_bf16_f32 v45, v48, v49
	v_exp_f32_e32 v50, v50
	v_exp_f32_e32 v51, v51
	s_waitcnt lgkmcnt(4)
	v_mfma_f32_32x32x16_bf16 v[66:81], v[146:149], v[114:117], v[66:81]
	ds_read_b128 v[170:173], v221 offset:32
	v_exp_f32_e32 v52, v52
	v_exp_f32_e32 v53, v53
	v_add_f32_e32 v231, v231, v50
	v_mfma_f32_32x32x16_bf16 v[82:97], v[150:153], v[114:117], v[82:97]
	ds_read_b128 v[174:177], v221 offset:4640
	v_add_f32_e32 v232, v232, v51
	v_exp_f32_e32 v54, v54
	v_exp_f32_e32 v55, v55
	v_add_f32_e32 v231, v231, v52
	v_add_f32_e32 v232, v232, v53
	s_waitcnt lgkmcnt(4)
	v_mfma_f32_32x32x16_bf16 v[66:81], v[154:157], v[118:121], v[66:81]
	ds_read_b128 v[180:183], v221 offset:64
	v_exp_f32_e32 v56, v56
	v_exp_f32_e32 v57, v57
	v_add_f32_e32 v231, v231, v54
	v_add_f32_e32 v232, v232, v55
	v_mfma_f32_32x32x16_bf16 v[82:97], v[158:161], v[118:121], v[82:97]
	ds_read_b128 v[184:187], v221 offset:4672
	v_add_f32_e32 v231, v231, v56
	v_add_f32_e32 v232, v232, v57
	v_cvt_pk_bf16_f32 v50, v50, v51
	v_cvt_pk_bf16_f32 v51, v52, v53
	v_cvt_pk_bf16_f32 v52, v54, v55
	v_cvt_pk_bf16_f32 v53, v56, v57
	s_waitcnt lgkmcnt(4)
	v_mfma_f32_32x32x16_bf16 v[2:17], v[162:165], v[34:37], v[2:17]
	ds_read_b128 v[188:191], v221 offset:96
	v_exp_f32_e32 v58, v58
	v_exp_f32_e32 v59, v59
	v_exp_f32_e32 v60, v60
	v_exp_f32_e32 v61, v61
	v_mfma_f32_32x32x16_bf16 v[18:33], v[166:169], v[34:37], v[18:33]
	ds_read_b128 v[192:195], v221 offset:4704
	v_add_f32_e32 v231, v231, v58
	v_add_f32_e32 v232, v232, v59
	v_exp_f32_e32 v62, v62
	v_exp_f32_e32 v63, v63
	s_waitcnt lgkmcnt(4)
	v_mfma_f32_32x32x16_bf16 v[2:17], v[170:173], v[42:45], v[2:17]
	v_add_f32_e32 v231, v231, v60
	v_add_f32_e32 v232, v232, v61
	v_exp_f32_e32 v64, v64
	v_exp_f32_e32 v65, v65
	v_mfma_f32_32x32x16_bf16 v[18:33], v[174:177], v[42:45], v[18:33]
	s_waitcnt vmcnt(4)
	ds_write_b64 v225, v[216:217] offset:18432
	ds_write_b64 v225, v[218:219] offset:18448
	v_add_f32_e32 v231, v231, v62
	v_add_f32_e32 v232, v232, v63
	v_add_f32_e32 v231, v231, v64
	v_add_f32_e32 v232, v232, v65
	v_cvt_pk_bf16_f32 v58, v58, v59
	v_cvt_pk_bf16_f32 v59, v60, v61
	s_waitcnt lgkmcnt(4)
	v_mfma_f32_32x32x16_bf16 v[2:17], v[180:183], v[50:53], v[2:17]
	v_cvt_pk_bf16_f32 v60, v62, v63
	v_cvt_pk_bf16_f32 v61, v64, v65
	v_max3_f32 v234, v66, v67, v68
	v_max3_f32 v235, v82, v83, v84
	v_max3_f32 v234, v234, v69, v70
	v_max3_f32 v235, v235, v85, v86
	v_mfma_f32_32x32x16_bf16 v[18:33], v[184:187], v[50:53], v[18:33]
	v_max3_f32 v234, v234, v71, v72
	v_max3_f32 v235, v235, v87, v88
	v_max3_f32 v234, v234, v73, v74
	v_max3_f32 v235, v235, v89, v90
	v_max3_f32 v234, v234, v75, v76
	v_max3_f32 v235, v235, v91, v92
	s_waitcnt lgkmcnt(2)
	v_mfma_f32_32x32x16_bf16 v[2:17], v[188:191], v[58:61], v[2:17]
	v_max3_f32 v234, v234, v77, v78
	v_max3_f32 v235, v235, v93, v94
	v_max3_f32 v234, v234, v79, v80
	v_max3_f32 v235, v235, v95, v96
	v_max3_f32 v234, v234, v81, v97
	v_max_f32_e32 v234, v234, v235
	v_mfma_f32_32x32x16_bf16 v[18:33], v[192:195], v[58:61], v[18:33]
	v_mov_b32_e32 v235, v234
	s_nop 1
	v_permlane32_swap_b32_e32 v234, v235
	v_max_f32_e32 v233, v234, v235
	v_cmp_lt_f32_e32 vcc, 4.0, v233
	s_cbranch_vccz .Lmls_nr_p0
	s_nop 15
	v_max_f32_e32 v234, 0, v233
	v_exp_f32_e64 v235, -v234
	v_add_f32_e32 v230, v230, v234
	v_sub_f32_e32 v66, v66, v234
	v_sub_f32_e32 v67, v67, v234
	v_sub_f32_e32 v68, v68, v234
	v_sub_f32_e32 v69, v69, v234
	v_sub_f32_e32 v70, v70, v234
	v_sub_f32_e32 v71, v71, v234
	v_sub_f32_e32 v72, v72, v234
	v_sub_f32_e32 v73, v73, v234
	v_sub_f32_e32 v74, v74, v234
	v_sub_f32_e32 v75, v75, v234
	v_sub_f32_e32 v76, v76, v234
	v_sub_f32_e32 v77, v77, v234
	v_sub_f32_e32 v78, v78, v234
	v_sub_f32_e32 v79, v79, v234
	v_sub_f32_e32 v80, v80, v234
	v_sub_f32_e32 v81, v81, v234
	v_sub_f32_e32 v82, v82, v234
	v_sub_f32_e32 v83, v83, v234
	v_sub_f32_e32 v84, v84, v234
	v_sub_f32_e32 v85, v85, v234
	v_sub_f32_e32 v86, v86, v234
	v_sub_f32_e32 v87, v87, v234
	v_sub_f32_e32 v88, v88, v234
	v_sub_f32_e32 v89, v89, v234
	v_sub_f32_e32 v90, v90, v234
	v_sub_f32_e32 v91, v91, v234
	v_sub_f32_e32 v92, v92, v234
	v_sub_f32_e32 v93, v93, v234
	v_sub_f32_e32 v94, v94, v234
	v_sub_f32_e32 v95, v95, v234
	v_sub_f32_e32 v96, v96, v234
	v_sub_f32_e32 v97, v97, v234
	v_mul_f32_e32 v231, v231, v235
	v_mul_f32_e32 v232, v232, v235
	v_mul_f32_e32 v2, v2, v235
	v_mul_f32_e32 v3, v3, v235
	v_mul_f32_e32 v4, v4, v235
	v_mul_f32_e32 v5, v5, v235
	v_mul_f32_e32 v6, v6, v235
	v_mul_f32_e32 v7, v7, v235
	v_mul_f32_e32 v8, v8, v235
	v_mul_f32_e32 v9, v9, v235
	v_mul_f32_e32 v10, v10, v235
	v_mul_f32_e32 v11, v11, v235
	v_mul_f32_e32 v12, v12, v235
	v_mul_f32_e32 v13, v13, v235
	v_mul_f32_e32 v14, v14, v235
	v_mul_f32_e32 v15, v15, v235
	v_mul_f32_e32 v16, v16, v235
	v_mul_f32_e32 v17, v17, v235
	v_mul_f32_e32 v18, v18, v235
	v_mul_f32_e32 v19, v19, v235
	v_mul_f32_e32 v20, v20, v235
	v_mul_f32_e32 v21, v21, v235
	v_mul_f32_e32 v22, v22, v235
	v_mul_f32_e32 v23, v23, v235
	v_mul_f32_e32 v24, v24, v235
	v_mul_f32_e32 v25, v25, v235
	v_mul_f32_e32 v26, v26, v235
	v_mul_f32_e32 v27, v27, v235
	v_mul_f32_e32 v28, v28, v235
	v_mul_f32_e32 v29, v29, v235
	v_mul_f32_e32 v30, v30, v235
	v_mul_f32_e32 v31, v31, v235
	v_mul_f32_e32 v32, v32, v235
	v_mul_f32_e32 v33, v33, v235
	v_sub_f32_e32 v122, 0, v230
	v_mov_b32_e32 v123, v122
	v_mov_b32_e32 v124, v122
	v_mov_b32_e32 v125, v122
	v_mov_b32_e32 v126, v122
	v_mov_b32_e32 v127, v122
	v_mov_b32_e32 v128, v122
	v_mov_b32_e32 v129, v122
	v_mov_b32_e32 v130, v122
	v_mov_b32_e32 v131, v122
	v_mov_b32_e32 v132, v122
	v_mov_b32_e32 v133, v122
	v_mov_b32_e32 v134, v122
	v_mov_b32_e32 v135, v122
	v_mov_b32_e32 v136, v122
	v_mov_b32_e32 v137, v122
.Lmls_nr_p0:
	ds_read_b128 v[138:141], v220 offset:26624
	ds_read_b128 v[142:145], v220 offset:33280
	ds_read_b128 v[146:149], v220 offset:26656
	ds_read_b128 v[150:153], v220 offset:33312
	ds_read_b128 v[154:157], v220 offset:26688
	ds_read_b128 v[158:161], v220 offset:33344
	s_waitcnt lgkmcnt(6)
	s_barrier
	v_exp_f32_e32 v66, v66
	v_exp_f32_e32 v67, v67
	v_exp_f32_e32 v68, v68
	v_exp_f32_e32 v69, v69
	s_waitcnt lgkmcnt(4)
	v_mfma_f32_32x32x16_bf16 v[34:49], v[138:141], v[98:101], v[122:137]
	ds_read_b128 v[138:141], v220 offset:26720
	v_add_f32_e32 v231, v231, v66
	v_add_f32_e32 v232, v232, v67
	v_exp_f32_e32 v70, v70
	v_exp_f32_e32 v71, v71
	v_mfma_f32_32x32x16_bf16 v[50:65], v[142:145], v[98:101], v[122:137]
	ds_read_b128 v[142:145], v220 offset:33376
	v_add_f32_e32 v231, v231, v68
	v_add_f32_e32 v232, v232, v69
	v_exp_f32_e32 v72, v72
	v_exp_f32_e32 v73, v73
	v_add_f32_e32 v231, v231, v70
	s_waitcnt lgkmcnt(4)
	v_mfma_f32_32x32x16_bf16 v[34:49], v[146:149], v[102:105], v[34:49]
	ds_read_b128 v[146:149], v220 offset:26752
	global_load_dwordx4 v[216:219], v229, s[10:11]
	s_add_u32 s10, s10, 0x80
	s_addc_u32 s11, s11, 0
	v_add_f32_e32 v232, v232, v71
	v_add_f32_e32 v231, v231, v72
	v_add_f32_e32 v232, v232, v73
	v_cvt_pk_bf16_f32 v66, v66, v67
	v_cvt_pk_bf16_f32 v67, v68, v69
	v_mfma_f32_32x32x16_bf16 v[50:65], v[150:153], v[102:105], v[50:65]
	ds_read_b128 v[150:153], v220 offset:33408
	v_cvt_pk_bf16_f32 v68, v70, v71
	v_cvt_pk_bf16_f32 v69, v72, v73
	v_exp_f32_e32 v74, v74
	v_exp_f32_e32 v75, v75
	v_exp_f32_e32 v76, v76
	s_waitcnt lgkmcnt(4)
	v_mfma_f32_32x32x16_bf16 v[34:49], v[154:157], v[106:109], v[34:49]
	ds_read_b128 v[154:157], v220 offset:26784
	v_exp_f32_e32 v77, v77
	v_add_f32_e32 v231, v231, v74
	v_add_f32_e32 v232, v232, v75
	v_exp_f32_e32 v78, v78
	v_mfma_f32_32x32x16_bf16 v[50:65], v[158:161], v[106:109], v[50:65]
	ds_read_b128 v[158:161], v220 offset:33440
	v_exp_f32_e32 v79, v79
	v_add_f32_e32 v231, v231, v76
	v_add_f32_e32 v232, v232, v77
	v_exp_f32_e32 v80, v80
	s_waitcnt lgkmcnt(4)
	v_mfma_f32_32x32x16_bf16 v[34:49], v[138:141], v[110:113], v[34:49]
	ds_read_b128 v[162:165], v221 offset:9216
	v_exp_f32_e32 v81, v81
	v_add_f32_e32 v231, v231, v78
	v_add_f32_e32 v232, v232, v79
	v_add_f32_e32 v231, v231, v80
	v_add_f32_e32 v232, v232, v81
	v_mfma_f32_32x32x16_bf16 v[50:65], v[142:145], v[110:113], v[50:65]
	ds_read_b128 v[166:169], v221 offset:13824
	v_cvt_pk_bf16_f32 v74, v74, v75
	v_cvt_pk_bf16_f32 v75, v76, v77
	v_cvt_pk_bf16_f32 v76, v78, v79
	v_cvt_pk_bf16_f32 v77, v80, v81
	v_exp_f32_e32 v82, v82
	v_exp_f32_e32 v83, v83
	s_waitcnt lgkmcnt(4)
	v_mfma_f32_32x32x16_bf16 v[34:49], v[146:149], v[114:117], v[34:49]
	ds_read_b128 v[170:173], v221 offset:9248
	v_exp_f32_e32 v84, v84
	v_exp_f32_e32 v85, v85
	v_add_f32_e32 v231, v231, v82
	v_mfma_f32_32x32x16_bf16 v[50:65], v[150:153], v[114:117], v[50:65]
	ds_read_b128 v[174:177], v221 offset:13856
	v_add_f32_e32 v232, v232, v83
	v_exp_f32_e32 v86, v86
	v_exp_f32_e32 v87, v87
	v_add_f32_e32 v231, v231, v84
	v_add_f32_e32 v232, v232, v85
	s_waitcnt lgkmcnt(4)
	v_mfma_f32_32x32x16_bf16 v[34:49], v[154:157], v[118:121], v[34:49]
	ds_read_b128 v[180:183], v221 offset:9280
	v_exp_f32_e32 v88, v88
	v_exp_f32_e32 v89, v89
	v_add_f32_e32 v231, v231, v86
	v_add_f32_e32 v232, v232, v87
	v_mfma_f32_32x32x16_bf16 v[50:65], v[158:161], v[118:121], v[50:65]
	ds_read_b128 v[184:187], v221 offset:13888
	v_add_f32_e32 v231, v231, v88
	v_add_f32_e32 v232, v232, v89
	v_cvt_pk_bf16_f32 v82, v82, v83
	v_cvt_pk_bf16_f32 v83, v84, v85
	v_cvt_pk_bf16_f32 v84, v86, v87
	v_cvt_pk_bf16_f32 v85, v88, v89
	s_waitcnt lgkmcnt(4)
	v_mfma_f32_32x32x16_bf16 v[2:17], v[162:165], v[66:69], v[2:17]
	ds_read_b128 v[188:191], v221 offset:9312
	v_exp_f32_e32 v90, v90
	v_exp_f32_e32 v91, v91
	v_exp_f32_e32 v92, v92
	v_exp_f32_e32 v93, v93
	v_mfma_f32_32x32x16_bf16 v[18:33], v[166:169], v[66:69], v[18:33]
	ds_read_b128 v[192:195], v221 offset:13920
	v_add_f32_e32 v231, v231, v90
	v_add_f32_e32 v232, v232, v91
	v_exp_f32_e32 v94, v94
	v_exp_f32_e32 v95, v95
	s_waitcnt lgkmcnt(4)
	v_mfma_f32_32x32x16_bf16 v[2:17], v[170:173], v[74:77], v[2:17]
	v_add_f32_e32 v231, v231, v92
	v_add_f32_e32 v232, v232, v93
	v_exp_f32_e32 v96, v96
	v_exp_f32_e32 v97, v97
	v_mfma_f32_32x32x16_bf16 v[18:33], v[174:177], v[74:77], v[18:33]
	s_waitcnt vmcnt(1)
	ds_write_b128 v222, v[200:203] offset:0
	ds_write_b128 v223, v[204:207] offset:0
	ds_write_b128 v224, v[208:211] offset:0
	ds_write_b64 v225, v[212:213] offset:27648
	ds_write_b64 v225, v[214:215] offset:27664
	v_add_f32_e32 v231, v231, v94
	v_add_f32_e32 v232, v232, v95
	v_add_f32_e32 v231, v231, v96
	v_add_f32_e32 v232, v232, v97
	v_cvt_pk_bf16_f32 v90, v90, v91
	v_cvt_pk_bf16_f32 v91, v92, v93
	s_waitcnt lgkmcnt(7)
	v_mfma_f32_32x32x16_bf16 v[2:17], v[180:183], v[82:85], v[2:17]
	v_cvt_pk_bf16_f32 v92, v94, v95
	v_cvt_pk_bf16_f32 v93, v96, v97
	v_max3_f32 v234, v34, v35, v36
	v_max3_f32 v235, v50, v51, v52
	v_max3_f32 v234, v234, v37, v38
	v_max3_f32 v235, v235, v53, v54
	v_mfma_f32_32x32x16_bf16 v[18:33], v[184:187], v[82:85], v[18:33]
	v_max3_f32 v234, v234, v39, v40
	v_max3_f32 v235, v235, v55, v56
	v_max3_f32 v234, v234, v41, v42
	v_max3_f32 v235, v235, v57, v58
	v_max3_f32 v234, v234, v43, v44
	v_max3_f32 v235, v235, v59, v60
	s_waitcnt lgkmcnt(5)
	v_mfma_f32_32x32x16_bf16 v[2:17], v[188:191], v[90:93], v[2:17]
	v_max3_f32 v234, v234, v45, v46
	v_max3_f32 v235, v235, v61, v62
	v_max3_f32 v234, v234, v47, v48
	v_max3_f32 v235, v235, v63, v64
	v_max3_f32 v234, v234, v49, v65
	v_max_f32_e32 v234, v234, v235
	v_mfma_f32_32x32x16_bf16 v[18:33], v[192:195], v[90:93], v[18:33]
	v_mov_b32_e32 v235, v234
	s_nop 1
	v_permlane32_swap_b32_e32 v234, v235
	v_max_f32_e32 v233, v234, v235
	v_cmp_lt_f32_e32 vcc, 4.0, v233
	s_cbranch_vccz .Lmls_nr_p1
	s_nop 15
	v_max_f32_e32 v234, 0, v233
	v_exp_f32_e64 v235, -v234
	v_add_f32_e32 v230, v230, v234
	v_sub_f32_e32 v34, v34, v234
	v_sub_f32_e32 v35, v35, v234
	v_sub_f32_e32 v36, v36, v234
	v_sub_f32_e32 v37, v37, v234
	v_sub_f32_e32 v38, v38, v234
	v_sub_f32_e32 v39, v39, v234
	v_sub_f32_e32 v40, v40, v234
	v_sub_f32_e32 v41, v41, v234
	v_sub_f32_e32 v42, v42, v234
	v_sub_f32_e32 v43, v43, v234
	v_sub_f32_e32 v44, v44, v234
	v_sub_f32_e32 v45, v45, v234
	v_sub_f32_e32 v46, v46, v234
	v_sub_f32_e32 v47, v47, v234
	v_sub_f32_e32 v48, v48, v234
	v_sub_f32_e32 v49, v49, v234
	v_sub_f32_e32 v50, v50, v234
	v_sub_f32_e32 v51, v51, v234
	v_sub_f32_e32 v52, v52, v234
	v_sub_f32_e32 v53, v53, v234
	v_sub_f32_e32 v54, v54, v234
	v_sub_f32_e32 v55, v55, v234
	v_sub_f32_e32 v56, v56, v234
	v_sub_f32_e32 v57, v57, v234
	v_sub_f32_e32 v58, v58, v234
	v_sub_f32_e32 v59, v59, v234
	v_sub_f32_e32 v60, v60, v234
	v_sub_f32_e32 v61, v61, v234
	v_sub_f32_e32 v62, v62, v234
	v_sub_f32_e32 v63, v63, v234
	v_sub_f32_e32 v64, v64, v234
	v_sub_f32_e32 v65, v65, v234
	v_mul_f32_e32 v231, v231, v235
	v_mul_f32_e32 v232, v232, v235
	v_mul_f32_e32 v2, v2, v235
	v_mul_f32_e32 v3, v3, v235
	v_mul_f32_e32 v4, v4, v235
	v_mul_f32_e32 v5, v5, v235
	v_mul_f32_e32 v6, v6, v235
	v_mul_f32_e32 v7, v7, v235
	v_mul_f32_e32 v8, v8, v235
	v_mul_f32_e32 v9, v9, v235
	v_mul_f32_e32 v10, v10, v235
	v_mul_f32_e32 v11, v11, v235
	v_mul_f32_e32 v12, v12, v235
	v_mul_f32_e32 v13, v13, v235
	v_mul_f32_e32 v14, v14, v235
	v_mul_f32_e32 v15, v15, v235
	v_mul_f32_e32 v16, v16, v235
	v_mul_f32_e32 v17, v17, v235
	v_mul_f32_e32 v18, v18, v235
	v_mul_f32_e32 v19, v19, v235
	v_mul_f32_e32 v20, v20, v235
	v_mul_f32_e32 v21, v21, v235
	v_mul_f32_e32 v22, v22, v235
	v_mul_f32_e32 v23, v23, v235
	v_mul_f32_e32 v24, v24, v235
	v_mul_f32_e32 v25, v25, v235
	v_mul_f32_e32 v26, v26, v235
	v_mul_f32_e32 v27, v27, v235
	v_mul_f32_e32 v28, v28, v235
	v_mul_f32_e32 v29, v29, v235
	v_mul_f32_e32 v30, v30, v235
	v_mul_f32_e32 v31, v31, v235
	v_mul_f32_e32 v32, v32, v235
	v_mul_f32_e32 v33, v33, v235
	v_sub_f32_e32 v122, 0, v230
	v_mov_b32_e32 v123, v122
	v_mov_b32_e32 v124, v122
	v_mov_b32_e32 v125, v122
	v_mov_b32_e32 v126, v122
	v_mov_b32_e32 v127, v122
	v_mov_b32_e32 v128, v122
	v_mov_b32_e32 v129, v122
	v_mov_b32_e32 v130, v122
	v_mov_b32_e32 v131, v122
	v_mov_b32_e32 v132, v122
	v_mov_b32_e32 v133, v122
	v_mov_b32_e32 v134, v122
	v_mov_b32_e32 v135, v122
	v_mov_b32_e32 v136, v122
	v_mov_b32_e32 v137, v122
.Lmls_nr_p1:
	ds_read_b128 v[138:141], v220 offset:39936
	ds_read_b128 v[142:145], v220 offset:46592
	ds_read_b128 v[146:149], v220 offset:39968
	ds_read_b128 v[150:153], v220 offset:46624
	ds_read_b128 v[154:157], v220 offset:40000
	ds_read_b128 v[158:161], v220 offset:46656
	s_waitcnt lgkmcnt(6)
	s_barrier
	v_exp_f32_e32 v34, v34
	v_exp_f32_e32 v35, v35
	v_exp_f32_e32 v36, v36
	v_exp_f32_e32 v37, v37
	s_waitcnt lgkmcnt(4)
	v_mfma_f32_32x32x16_bf16 v[66:81], v[138:141], v[98:101], v[122:137]
	ds_read_b128 v[138:141], v220 offset:40032
	v_add_f32_e32 v231, v231, v34
	v_add_f32_e32 v232, v232, v35
	v_exp_f32_e32 v38, v38
	v_exp_f32_e32 v39, v39
	v_mfma_f32_32x32x16_bf16 v[82:97], v[142:145], v[98:101], v[122:137]
	ds_read_b128 v[142:145], v220 offset:46688
	v_add_f32_e32 v231, v231, v36
	v_add_f32_e32 v232, v232, v37
	v_exp_f32_e32 v40, v40
	v_exp_f32_e32 v41, v41
	v_add_f32_e32 v231, v231, v38
	s_waitcnt lgkmcnt(4)
	v_mfma_f32_32x32x16_bf16 v[66:81], v[146:149], v[102:105], v[66:81]
	ds_read_b128 v[146:149], v220 offset:40064
	global_load_dwordx4 v[200:203], v226, s[4:5]
	global_load_dwordx4 v[204:207], v227, s[4:5]
	global_load_dwordx4 v[208:211], v228, s[4:5]
	s_add_u32 s4, s4, 0x6000
	s_addc_u32 s5, s5, 0
	global_load_dwordx4 v[212:215], v229, s[10:11]
	s_add_u32 s10, s10, 0x80
	s_addc_u32 s11, s11, 0
	v_add_f32_e32 v232, v232, v39
	v_add_f32_e32 v231, v231, v40
	v_add_f32_e32 v232, v232, v41
	v_cvt_pk_bf16_f32 v34, v34, v35
	v_cvt_pk_bf16_f32 v35, v36, v37
	v_mfma_f32_32x32x16_bf16 v[82:97], v[150:153], v[102:105], v[82:97]
	ds_read_b128 v[150:153], v220 offset:46720
	v_cvt_pk_bf16_f32 v36, v38, v39
	v_cvt_pk_bf16_f32 v37, v40, v41
	v_exp_f32_e32 v42, v42
	v_exp_f32_e32 v43, v43
	v_exp_f32_e32 v44, v44
	s_waitcnt lgkmcnt(4)
	v_mfma_f32_32x32x16_bf16 v[66:81], v[154:157], v[106:109], v[66:81]
	ds_read_b128 v[154:157], v220 offset:40096
	v_exp_f32_e32 v45, v45
	v_add_f32_e32 v231, v231, v42
	v_add_f32_e32 v232, v232, v43
	v_exp_f32_e32 v46, v46
	v_mfma_f32_32x32x16_bf16 v[82:97], v[158:161], v[106:109], v[82:97]
	ds_read_b128 v[158:161], v220 offset:46752
	v_exp_f32_e32 v47, v47
	v_add_f32_e32 v231, v231, v44
	v_add_f32_e32 v232, v232, v45
	v_exp_f32_e32 v48, v48
	s_waitcnt lgkmcnt(4)
	v_mfma_f32_32x32x16_bf16 v[66:81], v[138:141], v[110:113], v[66:81]
	ds_read_b128 v[162:165], v221 offset:18432
	v_exp_f32_e32 v49, v49
	v_add_f32_e32 v231, v231, v46
	v_add_f32_e32 v232, v232, v47
	v_add_f32_e32 v231, v231, v48
	v_add_f32_e32 v232, v232, v49
	v_mfma_f32_32x32x16_bf16 v[82:97], v[142:145], v[110:113], v[82:97]
	ds_read_b128 v[166:169], v221 offset:23040
	v_cvt_pk_bf16_f32 v42, v42, v43
	v_cvt_pk_bf16_f32 v43, v44, v45
	v_cvt_pk_bf16_f32 v44, v46, v47
	v_cvt_pk_bf16_f32 v45, v48, v49
	v_exp_f32_e32 v50, v50
	v_exp_f32_e32 v51, v51
	s_waitcnt lgkmcnt(4)
	v_mfma_f32_32x32x16_bf16 v[66:81], v[146:149], v[114:117], v[66:81]
	ds_read_b128 v[170:173], v221 offset:18464
	v_exp_f32_e32 v52, v52
	v_exp_f32_e32 v53, v53
	v_add_f32_e32 v231, v231, v50
	v_mfma_f32_32x32x16_bf16 v[82:97], v[150:153], v[114:117], v[82:97]
	ds_read_b128 v[174:177], v221 offset:23072
	v_add_f32_e32 v232, v232, v51
	v_exp_f32_e32 v54, v54
	v_exp_f32_e32 v55, v55
	v_add_f32_e32 v231, v231, v52
	v_add_f32_e32 v232, v232, v53
	s_waitcnt lgkmcnt(4)
	v_mfma_f32_32x32x16_bf16 v[66:81], v[154:157], v[118:121], v[66:81]
	ds_read_b128 v[180:183], v221 offset:18496
	v_exp_f32_e32 v56, v56
	v_exp_f32_e32 v57, v57
	v_add_f32_e32 v231, v231, v54
	v_add_f32_e32 v232, v232, v55
	v_mfma_f32_32x32x16_bf16 v[82:97], v[158:161], v[118:121], v[82:97]
	ds_read_b128 v[184:187], v221 offset:23104
	v_add_f32_e32 v231, v231, v56
	v_add_f32_e32 v232, v232, v57
	v_cvt_pk_bf16_f32 v50, v50, v51
	v_cvt_pk_bf16_f32 v51, v52, v53
	v_cvt_pk_bf16_f32 v52, v54, v55
	v_cvt_pk_bf16_f32 v53, v56, v57
	s_waitcnt lgkmcnt(4)
	v_mfma_f32_32x32x16_bf16 v[2:17], v[162:165], v[34:37], v[2:17]
	ds_read_b128 v[188:191], v221 offset:18528
	v_exp_f32_e32 v58, v58
	v_exp_f32_e32 v59, v59
	v_exp_f32_e32 v60, v60
	v_exp_f32_e32 v61, v61
	v_mfma_f32_32x32x16_bf16 v[18:33], v[166:169], v[34:37], v[18:33]
	ds_read_b128 v[192:195], v221 offset:23136
	v_add_f32_e32 v231, v231, v58
	v_add_f32_e32 v232, v232, v59
	v_exp_f32_e32 v62, v62
	v_exp_f32_e32 v63, v63
	s_waitcnt lgkmcnt(4)
	v_mfma_f32_32x32x16_bf16 v[2:17], v[170:173], v[42:45], v[2:17]
	v_add_f32_e32 v231, v231, v60
	v_add_f32_e32 v232, v232, v61
	v_exp_f32_e32 v64, v64
	v_exp_f32_e32 v65, v65
	v_mfma_f32_32x32x16_bf16 v[18:33], v[174:177], v[42:45], v[18:33]
	s_waitcnt vmcnt(4)
	ds_write_b64 v225, v[216:217] offset:0
	ds_write_b64 v225, v[218:219] offset:16
	v_add_f32_e32 v231, v231, v62
	v_add_f32_e32 v232, v232, v63
	v_add_f32_e32 v231, v231, v64
	v_add_f32_e32 v232, v232, v65
	v_cvt_pk_bf16_f32 v58, v58, v59
	v_cvt_pk_bf16_f32 v59, v60, v61
	s_waitcnt lgkmcnt(4)
	v_mfma_f32_32x32x16_bf16 v[2:17], v[180:183], v[50:53], v[2:17]
	v_cvt_pk_bf16_f32 v60, v62, v63
	v_cvt_pk_bf16_f32 v61, v64, v65
	v_max3_f32 v234, v66, v67, v68
	v_max3_f32 v235, v82, v83, v84
	v_max3_f32 v234, v234, v69, v70
	v_max3_f32 v235, v235, v85, v86
	v_mfma_f32_32x32x16_bf16 v[18:33], v[184:187], v[50:53], v[18:33]
	v_max3_f32 v234, v234, v71, v72
	v_max3_f32 v235, v235, v87, v88
	v_max3_f32 v234, v234, v73, v74
	v_max3_f32 v235, v235, v89, v90
	v_max3_f32 v234, v234, v75, v76
	v_max3_f32 v235, v235, v91, v92
	s_waitcnt lgkmcnt(2)
	v_mfma_f32_32x32x16_bf16 v[2:17], v[188:191], v[58:61], v[2:17]
	v_max3_f32 v234, v234, v77, v78
	v_max3_f32 v235, v235, v93, v94
	v_max3_f32 v234, v234, v79, v80
	v_max3_f32 v235, v235, v95, v96
	v_max3_f32 v234, v234, v81, v97
	v_max_f32_e32 v234, v234, v235
	v_mfma_f32_32x32x16_bf16 v[18:33], v[192:195], v[58:61], v[18:33]
	v_mov_b32_e32 v235, v234
	s_nop 1
	v_permlane32_swap_b32_e32 v234, v235
	v_max_f32_e32 v233, v234, v235
	v_cmp_lt_f32_e32 vcc, 4.0, v233
	s_cbranch_vccz .Lmls_nr_p2
	s_nop 15
	v_max_f32_e32 v234, 0, v233
	v_exp_f32_e64 v235, -v234
	v_add_f32_e32 v230, v230, v234
	v_sub_f32_e32 v66, v66, v234
	v_sub_f32_e32 v67, v67, v234
	v_sub_f32_e32 v68, v68, v234
	v_sub_f32_e32 v69, v69, v234
	v_sub_f32_e32 v70, v70, v234
	v_sub_f32_e32 v71, v71, v234
	v_sub_f32_e32 v72, v72, v234
	v_sub_f32_e32 v73, v73, v234
	v_sub_f32_e32 v74, v74, v234
	v_sub_f32_e32 v75, v75, v234
	v_sub_f32_e32 v76, v76, v234
	v_sub_f32_e32 v77, v77, v234
	v_sub_f32_e32 v78, v78, v234
	v_sub_f32_e32 v79, v79, v234
	v_sub_f32_e32 v80, v80, v234
	v_sub_f32_e32 v81, v81, v234
	v_sub_f32_e32 v82, v82, v234
	v_sub_f32_e32 v83, v83, v234
	v_sub_f32_e32 v84, v84, v234
	v_sub_f32_e32 v85, v85, v234
	v_sub_f32_e32 v86, v86, v234
	v_sub_f32_e32 v87, v87, v234
	v_sub_f32_e32 v88, v88, v234
	v_sub_f32_e32 v89, v89, v234
	v_sub_f32_e32 v90, v90, v234
	v_sub_f32_e32 v91, v91, v234
	v_sub_f32_e32 v92, v92, v234
	v_sub_f32_e32 v93, v93, v234
	v_sub_f32_e32 v94, v94, v234
	v_sub_f32_e32 v95, v95, v234
	v_sub_f32_e32 v96, v96, v234
	v_sub_f32_e32 v97, v97, v234
	v_mul_f32_e32 v231, v231, v235
	v_mul_f32_e32 v232, v232, v235
	v_mul_f32_e32 v2, v2, v235
	v_mul_f32_e32 v3, v3, v235
	v_mul_f32_e32 v4, v4, v235
	v_mul_f32_e32 v5, v5, v235
	v_mul_f32_e32 v6, v6, v235
	v_mul_f32_e32 v7, v7, v235
	v_mul_f32_e32 v8, v8, v235
	v_mul_f32_e32 v9, v9, v235
	v_mul_f32_e32 v10, v10, v235
	v_mul_f32_e32 v11, v11, v235
	v_mul_f32_e32 v12, v12, v235
	v_mul_f32_e32 v13, v13, v235
	v_mul_f32_e32 v14, v14, v235
	v_mul_f32_e32 v15, v15, v235
	v_mul_f32_e32 v16, v16, v235
	v_mul_f32_e32 v17, v17, v235
	v_mul_f32_e32 v18, v18, v235
	v_mul_f32_e32 v19, v19, v235
	v_mul_f32_e32 v20, v20, v235
	v_mul_f32_e32 v21, v21, v235
	v_mul_f32_e32 v22, v22, v235
	v_mul_f32_e32 v23, v23, v235
	v_mul_f32_e32 v24, v24, v235
	v_mul_f32_e32 v25, v25, v235
	v_mul_f32_e32 v26, v26, v235
	v_mul_f32_e32 v27, v27, v235
	v_mul_f32_e32 v28, v28, v235
	v_mul_f32_e32 v29, v29, v235
	v_mul_f32_e32 v30, v30, v235
	v_mul_f32_e32 v31, v31, v235
	v_mul_f32_e32 v32, v32, v235
	v_mul_f32_e32 v33, v33, v235
	v_sub_f32_e32 v122, 0, v230
	v_mov_b32_e32 v123, v122
	v_mov_b32_e32 v124, v122
	v_mov_b32_e32 v125, v122
	v_mov_b32_e32 v126, v122
	v_mov_b32_e32 v127, v122
	v_mov_b32_e32 v128, v122
	v_mov_b32_e32 v129, v122
	v_mov_b32_e32 v130, v122
	v_mov_b32_e32 v131, v122
	v_mov_b32_e32 v132, v122
	v_mov_b32_e32 v133, v122
	v_mov_b32_e32 v134, v122
	v_mov_b32_e32 v135, v122
	v_mov_b32_e32 v136, v122
	v_mov_b32_e32 v137, v122
.Lmls_nr_p2:
	ds_read_b128 v[138:141], v220 offset:0
	ds_read_b128 v[142:145], v220 offset:6656
	ds_read_b128 v[146:149], v220 offset:32
	ds_read_b128 v[150:153], v220 offset:6688
	ds_read_b128 v[154:157], v220 offset:64
	ds_read_b128 v[158:161], v220 offset:6720
	s_waitcnt lgkmcnt(6)
	s_barrier
	v_exp_f32_e32 v66, v66
	v_exp_f32_e32 v67, v67
	v_exp_f32_e32 v68, v68
	v_exp_f32_e32 v69, v69
	s_waitcnt lgkmcnt(4)
	v_mfma_f32_32x32x16_bf16 v[34:49], v[138:141], v[98:101], v[122:137]
	ds_read_b128 v[138:141], v220 offset:96
	v_add_f32_e32 v231, v231, v66
	v_add_f32_e32 v232, v232, v67
	v_exp_f32_e32 v70, v70
	v_exp_f32_e32 v71, v71
	v_mfma_f32_32x32x16_bf16 v[50:65], v[142:145], v[98:101], v[122:137]
	ds_read_b128 v[142:145], v220 offset:6752
	v_add_f32_e32 v231, v231, v68
	v_add_f32_e32 v232, v232, v69
	v_exp_f32_e32 v72, v72
	v_exp_f32_e32 v73, v73
	v_add_f32_e32 v231, v231, v70
	s_waitcnt lgkmcnt(4)
	v_mfma_f32_32x32x16_bf16 v[34:49], v[146:149], v[102:105], v[34:49]
	ds_read_b128 v[146:149], v220 offset:128
	global_load_dwordx4 v[216:219], v229, s[10:11]
	s_add_u32 s10, s10, 0x80
	s_addc_u32 s11, s11, 0
	v_add_f32_e32 v232, v232, v71
	v_add_f32_e32 v231, v231, v72
	v_add_f32_e32 v232, v232, v73
	v_cvt_pk_bf16_f32 v66, v66, v67
	v_cvt_pk_bf16_f32 v67, v68, v69
	v_mfma_f32_32x32x16_bf16 v[50:65], v[150:153], v[102:105], v[50:65]
	ds_read_b128 v[150:153], v220 offset:6784
	v_cvt_pk_bf16_f32 v68, v70, v71
	v_cvt_pk_bf16_f32 v69, v72, v73
	v_exp_f32_e32 v74, v74
	v_exp_f32_e32 v75, v75
	v_exp_f32_e32 v76, v76
	s_waitcnt lgkmcnt(4)
	v_mfma_f32_32x32x16_bf16 v[34:49], v[154:157], v[106:109], v[34:49]
	ds_read_b128 v[154:157], v220 offset:160
	v_exp_f32_e32 v77, v77
	v_add_f32_e32 v231, v231, v74
	v_add_f32_e32 v232, v232, v75
	v_exp_f32_e32 v78, v78
	v_mfma_f32_32x32x16_bf16 v[50:65], v[158:161], v[106:109], v[50:65]
	ds_read_b128 v[158:161], v220 offset:6816
	v_exp_f32_e32 v79, v79
	v_add_f32_e32 v231, v231, v76
	v_add_f32_e32 v232, v232, v77
	v_exp_f32_e32 v80, v80
	s_waitcnt lgkmcnt(4)
	v_mfma_f32_32x32x16_bf16 v[34:49], v[138:141], v[110:113], v[34:49]
	ds_read_b128 v[162:165], v221 offset:27648
	v_exp_f32_e32 v81, v81
	v_add_f32_e32 v231, v231, v78
	v_add_f32_e32 v232, v232, v79
	v_add_f32_e32 v231, v231, v80
	v_add_f32_e32 v232, v232, v81
	v_mfma_f32_32x32x16_bf16 v[50:65], v[142:145], v[110:113], v[50:65]
	ds_read_b128 v[166:169], v221 offset:32256
	v_cvt_pk_bf16_f32 v74, v74, v75
	v_cvt_pk_bf16_f32 v75, v76, v77
	v_cvt_pk_bf16_f32 v76, v78, v79
	v_cvt_pk_bf16_f32 v77, v80, v81
	v_exp_f32_e32 v82, v82
	v_exp_f32_e32 v83, v83
	s_waitcnt lgkmcnt(4)
	v_mfma_f32_32x32x16_bf16 v[34:49], v[146:149], v[114:117], v[34:49]
	ds_read_b128 v[170:173], v221 offset:27680
	v_exp_f32_e32 v84, v84
	v_exp_f32_e32 v85, v85
	v_add_f32_e32 v231, v231, v82
	v_mfma_f32_32x32x16_bf16 v[50:65], v[150:153], v[114:117], v[50:65]
	ds_read_b128 v[174:177], v221 offset:32288
	v_add_f32_e32 v232, v232, v83
	v_exp_f32_e32 v86, v86
	v_exp_f32_e32 v87, v87
	v_add_f32_e32 v231, v231, v84
	v_add_f32_e32 v232, v232, v85
	s_waitcnt lgkmcnt(4)
	v_mfma_f32_32x32x16_bf16 v[34:49], v[154:157], v[118:121], v[34:49]
	ds_read_b128 v[180:183], v221 offset:27712
	v_exp_f32_e32 v88, v88
	v_exp_f32_e32 v89, v89
	v_add_f32_e32 v231, v231, v86
	v_add_f32_e32 v232, v232, v87
	v_mfma_f32_32x32x16_bf16 v[50:65], v[158:161], v[118:121], v[50:65]
	ds_read_b128 v[184:187], v221 offset:32320
	v_add_f32_e32 v231, v231, v88
	v_add_f32_e32 v232, v232, v89
	v_cvt_pk_bf16_f32 v82, v82, v83
	v_cvt_pk_bf16_f32 v83, v84, v85
	v_cvt_pk_bf16_f32 v84, v86, v87
	v_cvt_pk_bf16_f32 v85, v88, v89
	s_waitcnt lgkmcnt(4)
	v_mfma_f32_32x32x16_bf16 v[2:17], v[162:165], v[66:69], v[2:17]
	ds_read_b128 v[188:191], v221 offset:27744
	v_exp_f32_e32 v90, v90
	v_exp_f32_e32 v91, v91
	v_exp_f32_e32 v92, v92
	v_exp_f32_e32 v93, v93
	v_mfma_f32_32x32x16_bf16 v[18:33], v[166:169], v[66:69], v[18:33]
	ds_read_b128 v[192:195], v221 offset:32352
	v_add_f32_e32 v231, v231, v90
	v_add_f32_e32 v232, v232, v91
	v_exp_f32_e32 v94, v94
	v_exp_f32_e32 v95, v95
	s_waitcnt lgkmcnt(4)
	v_mfma_f32_32x32x16_bf16 v[2:17], v[170:173], v[74:77], v[2:17]
	v_add_f32_e32 v231, v231, v92
	v_add_f32_e32 v232, v232, v93
	v_exp_f32_e32 v96, v96
	v_exp_f32_e32 v97, v97
	v_mfma_f32_32x32x16_bf16 v[18:33], v[174:177], v[74:77], v[18:33]
	s_waitcnt vmcnt(1)
	ds_write_b128 v222, v[200:203] offset:26624
	ds_write_b128 v223, v[204:207] offset:26624
	ds_write_b128 v224, v[208:211] offset:26624
	ds_write_b64 v225, v[212:213] offset:9216
	ds_write_b64 v225, v[214:215] offset:9232
	v_add_f32_e32 v231, v231, v94
	v_add_f32_e32 v232, v232, v95
	v_add_f32_e32 v231, v231, v96
	v_add_f32_e32 v232, v232, v97
	v_cvt_pk_bf16_f32 v90, v90, v91
	v_cvt_pk_bf16_f32 v91, v92, v93
	s_waitcnt lgkmcnt(7)
	v_mfma_f32_32x32x16_bf16 v[2:17], v[180:183], v[82:85], v[2:17]
	v_cvt_pk_bf16_f32 v92, v94, v95
	v_cvt_pk_bf16_f32 v93, v96, v97
	v_max3_f32 v234, v34, v35, v36
	v_max3_f32 v235, v50, v51, v52
	v_max3_f32 v234, v234, v37, v38
	v_max3_f32 v235, v235, v53, v54
	v_mfma_f32_32x32x16_bf16 v[18:33], v[184:187], v[82:85], v[18:33]
	v_max3_f32 v234, v234, v39, v40
	v_max3_f32 v235, v235, v55, v56
	v_max3_f32 v234, v234, v41, v42
	v_max3_f32 v235, v235, v57, v58
	v_max3_f32 v234, v234, v43, v44
	v_max3_f32 v235, v235, v59, v60
	s_waitcnt lgkmcnt(5)
	v_mfma_f32_32x32x16_bf16 v[2:17], v[188:191], v[90:93], v[2:17]
	v_max3_f32 v234, v234, v45, v46
	v_max3_f32 v235, v235, v61, v62
	v_max3_f32 v234, v234, v47, v48
	v_max3_f32 v235, v235, v63, v64
	v_max3_f32 v234, v234, v49, v65
	v_max_f32_e32 v234, v234, v235
	v_mfma_f32_32x32x16_bf16 v[18:33], v[192:195], v[90:93], v[18:33]
	v_mov_b32_e32 v235, v234
	s_nop 1
	v_permlane32_swap_b32_e32 v234, v235
	v_max_f32_e32 v233, v234, v235
	v_cmp_lt_f32_e32 vcc, 4.0, v233
	s_cbranch_vccz .Lmls_nr_p3
	s_nop 15
	v_max_f32_e32 v234, 0, v233
	v_exp_f32_e64 v235, -v234
	v_add_f32_e32 v230, v230, v234
	v_sub_f32_e32 v34, v34, v234
	v_sub_f32_e32 v35, v35, v234
	v_sub_f32_e32 v36, v36, v234
	v_sub_f32_e32 v37, v37, v234
	v_sub_f32_e32 v38, v38, v234
	v_sub_f32_e32 v39, v39, v234
	v_sub_f32_e32 v40, v40, v234
	v_sub_f32_e32 v41, v41, v234
	v_sub_f32_e32 v42, v42, v234
	v_sub_f32_e32 v43, v43, v234
	v_sub_f32_e32 v44, v44, v234
	v_sub_f32_e32 v45, v45, v234
	v_sub_f32_e32 v46, v46, v234
	v_sub_f32_e32 v47, v47, v234
	v_sub_f32_e32 v48, v48, v234
	v_sub_f32_e32 v49, v49, v234
	v_sub_f32_e32 v50, v50, v234
	v_sub_f32_e32 v51, v51, v234
	v_sub_f32_e32 v52, v52, v234
	v_sub_f32_e32 v53, v53, v234
	v_sub_f32_e32 v54, v54, v234
	v_sub_f32_e32 v55, v55, v234
	v_sub_f32_e32 v56, v56, v234
	v_sub_f32_e32 v57, v57, v234
	v_sub_f32_e32 v58, v58, v234
	v_sub_f32_e32 v59, v59, v234
	v_sub_f32_e32 v60, v60, v234
	v_sub_f32_e32 v61, v61, v234
	v_sub_f32_e32 v62, v62, v234
	v_sub_f32_e32 v63, v63, v234
	v_sub_f32_e32 v64, v64, v234
	v_sub_f32_e32 v65, v65, v234
	v_mul_f32_e32 v231, v231, v235
	v_mul_f32_e32 v232, v232, v235
	v_mul_f32_e32 v2, v2, v235
	v_mul_f32_e32 v3, v3, v235
	v_mul_f32_e32 v4, v4, v235
	v_mul_f32_e32 v5, v5, v235
	v_mul_f32_e32 v6, v6, v235
	v_mul_f32_e32 v7, v7, v235
	v_mul_f32_e32 v8, v8, v235
	v_mul_f32_e32 v9, v9, v235
	v_mul_f32_e32 v10, v10, v235
	v_mul_f32_e32 v11, v11, v235
	v_mul_f32_e32 v12, v12, v235
	v_mul_f32_e32 v13, v13, v235
	v_mul_f32_e32 v14, v14, v235
	v_mul_f32_e32 v15, v15, v235
	v_mul_f32_e32 v16, v16, v235
	v_mul_f32_e32 v17, v17, v235
	v_mul_f32_e32 v18, v18, v235
	v_mul_f32_e32 v19, v19, v235
	v_mul_f32_e32 v20, v20, v235
	v_mul_f32_e32 v21, v21, v235
	v_mul_f32_e32 v22, v22, v235
	v_mul_f32_e32 v23, v23, v235
	v_mul_f32_e32 v24, v24, v235
	v_mul_f32_e32 v25, v25, v235
	v_mul_f32_e32 v26, v26, v235
	v_mul_f32_e32 v27, v27, v235
	v_mul_f32_e32 v28, v28, v235
	v_mul_f32_e32 v29, v29, v235
	v_mul_f32_e32 v30, v30, v235
	v_mul_f32_e32 v31, v31, v235
	v_mul_f32_e32 v32, v32, v235
	v_mul_f32_e32 v33, v33, v235
	v_sub_f32_e32 v122, 0, v230
	v_mov_b32_e32 v123, v122
	v_mov_b32_e32 v124, v122
	v_mov_b32_e32 v125, v122
	v_mov_b32_e32 v126, v122
	v_mov_b32_e32 v127, v122
	v_mov_b32_e32 v128, v122
	v_mov_b32_e32 v129, v122
	v_mov_b32_e32 v130, v122
	v_mov_b32_e32 v131, v122
	v_mov_b32_e32 v132, v122
	v_mov_b32_e32 v133, v122
	v_mov_b32_e32 v134, v122
	v_mov_b32_e32 v135, v122
	v_mov_b32_e32 v136, v122
	v_mov_b32_e32 v137, v122
.Lmls_nr_p3:
	ds_read_b128 v[138:141], v220 offset:13312
	ds_read_b128 v[142:145], v220 offset:19968
	ds_read_b128 v[146:149], v220 offset:13344
	ds_read_b128 v[150:153], v220 offset:20000
	ds_read_b128 v[154:157], v220 offset:13376
	ds_read_b128 v[158:161], v220 offset:20032
	s_waitcnt lgkmcnt(6)
	s_barrier
	s_add_i32 s16, s16, -1
	s_cmp_lg_u32 s16, 0
	s_cbranch_scc1 .Lmls_loop
	v_exp_f32_e32 v34, v34
	v_exp_f32_e32 v35, v35
	v_exp_f32_e32 v36, v36
	v_exp_f32_e32 v37, v37
	s_waitcnt lgkmcnt(4)
	v_mfma_f32_32x32x16_bf16 v[66:81], v[138:141], v[98:101], v[122:137]
	ds_read_b128 v[138:141], v220 offset:13408
	v_add_f32_e32 v231, v231, v34
	v_add_f32_e32 v232, v232, v35
	v_exp_f32_e32 v38, v38
	v_exp_f32_e32 v39, v39
	v_mfma_f32_32x32x16_bf16 v[82:97], v[142:145], v[98:101], v[122:137]
	ds_read_b128 v[142:145], v220 offset:20064
	v_add_f32_e32 v231, v231, v36
	v_add_f32_e32 v232, v232, v37
	v_exp_f32_e32 v40, v40
	v_exp_f32_e32 v41, v41
	v_add_f32_e32 v231, v231, v38
	s_waitcnt lgkmcnt(4)
	v_mfma_f32_32x32x16_bf16 v[66:81], v[146:149], v[102:105], v[66:81]
	ds_read_b128 v[146:149], v220 offset:13440
	global_load_dwordx4 v[212:215], v229, s[10:11]
	s_add_u32 s10, s10, 0x80
	s_addc_u32 s11, s11, 0
	v_add_f32_e32 v232, v232, v39
	v_add_f32_e32 v231, v231, v40
	v_add_f32_e32 v232, v232, v41
	v_cvt_pk_bf16_f32 v34, v34, v35
	v_cvt_pk_bf16_f32 v35, v36, v37
	v_mfma_f32_32x32x16_bf16 v[82:97], v[150:153], v[102:105], v[82:97]
	ds_read_b128 v[150:153], v220 offset:20096
	v_cvt_pk_bf16_f32 v36, v38, v39
	v_cvt_pk_bf16_f32 v37, v40, v41
	v_exp_f32_e32 v42, v42
	v_exp_f32_e32 v43, v43
	v_exp_f32_e32 v44, v44
	s_waitcnt lgkmcnt(4)
	v_mfma_f32_32x32x16_bf16 v[66:81], v[154:157], v[106:109], v[66:81]
	ds_read_b128 v[154:157], v220 offset:13472
	v_exp_f32_e32 v45, v45
	v_add_f32_e32 v231, v231, v42
	v_add_f32_e32 v232, v232, v43
	v_exp_f32_e32 v46, v46
	v_mfma_f32_32x32x16_bf16 v[82:97], v[158:161], v[106:109], v[82:97]
	ds_read_b128 v[158:161], v220 offset:20128
	v_exp_f32_e32 v47, v47
	v_add_f32_e32 v231, v231, v44
	v_add_f32_e32 v232, v232, v45
	v_exp_f32_e32 v48, v48
	s_waitcnt lgkmcnt(4)
	v_mfma_f32_32x32x16_bf16 v[66:81], v[138:141], v[110:113], v[66:81]
	ds_read_b128 v[162:165], v221 offset:0
	v_exp_f32_e32 v49, v49
	v_add_f32_e32 v231, v231, v46
	v_add_f32_e32 v232, v232, v47
	v_add_f32_e32 v231, v231, v48
	v_add_f32_e32 v232, v232, v49
	v_mfma_f32_32x32x16_bf16 v[82:97], v[142:145], v[110:113], v[82:97]
	ds_read_b128 v[166:169], v221 offset:4608
	v_cvt_pk_bf16_f32 v42, v42, v43
	v_cvt_pk_bf16_f32 v43, v44, v45
	v_cvt_pk_bf16_f32 v44, v46, v47
	v_cvt_pk_bf16_f32 v45, v48, v49
	v_exp_f32_e32 v50, v50
	v_exp_f32_e32 v51, v51
	s_waitcnt lgkmcnt(4)
	v_mfma_f32_32x32x16_bf16 v[66:81], v[146:149], v[114:117], v[66:81]
	ds_read_b128 v[170:173], v221 offset:32
	v_exp_f32_e32 v52, v52
	v_exp_f32_e32 v53, v53
	v_add_f32_e32 v231, v231, v50
	v_mfma_f32_32x32x16_bf16 v[82:97], v[150:153], v[114:117], v[82:97]
	ds_read_b128 v[174:177], v221 offset:4640
	v_add_f32_e32 v232, v232, v51
	v_exp_f32_e32 v54, v54
	v_exp_f32_e32 v55, v55
	v_add_f32_e32 v231, v231, v52
	v_add_f32_e32 v232, v232, v53
	s_waitcnt lgkmcnt(4)
	v_mfma_f32_32x32x16_bf16 v[66:81], v[154:157], v[118:121], v[66:81]
	ds_read_b128 v[180:183], v221 offset:64
	v_exp_f32_e32 v56, v56
	v_exp_f32_e32 v57, v57
	v_add_f32_e32 v231, v231, v54
	v_add_f32_e32 v232, v232, v55
	v_mfma_f32_32x32x16_bf16 v[82:97], v[158:161], v[118:121], v[82:97]
	ds_read_b128 v[184:187], v221 offset:4672
	v_add_f32_e32 v231, v231, v56
	v_add_f32_e32 v232, v232, v57
	v_cvt_pk_bf16_f32 v50, v50, v51
	v_cvt_pk_bf16_f32 v51, v52, v53
	v_cvt_pk_bf16_f32 v52, v54, v55
	v_cvt_pk_bf16_f32 v53, v56, v57
	s_waitcnt lgkmcnt(4)
	v_mfma_f32_32x32x16_bf16 v[2:17], v[162:165], v[34:37], v[2:17]
	ds_read_b128 v[188:191], v221 offset:96
	v_exp_f32_e32 v58, v58
	v_exp_f32_e32 v59, v59
	v_exp_f32_e32 v60, v60
	v_exp_f32_e32 v61, v61
	v_mfma_f32_32x32x16_bf16 v[18:33], v[166:169], v[34:37], v[18:33]
	ds_read_b128 v[192:195], v221 offset:4704
	v_add_f32_e32 v231, v231, v58
	v_add_f32_e32 v232, v232, v59
	v_exp_f32_e32 v62, v62
	v_exp_f32_e32 v63, v63
	s_waitcnt lgkmcnt(4)
	v_mfma_f32_32x32x16_bf16 v[2:17], v[170:173], v[42:45], v[2:17]
	v_add_f32_e32 v231, v231, v60
	v_add_f32_e32 v232, v232, v61
	v_exp_f32_e32 v64, v64
	v_exp_f32_e32 v65, v65
	v_mfma_f32_32x32x16_bf16 v[18:33], v[174:177], v[42:45], v[18:33]
	s_waitcnt vmcnt(1)
	ds_write_b64 v225, v[216:217] offset:18432
	ds_write_b64 v225, v[218:219] offset:18448
	v_add_f32_e32 v231, v231, v62
	v_add_f32_e32 v232, v232, v63
	v_add_f32_e32 v231, v231, v64
	v_add_f32_e32 v232, v232, v65
	v_cvt_pk_bf16_f32 v58, v58, v59
	v_cvt_pk_bf16_f32 v59, v60, v61
	s_waitcnt lgkmcnt(4)
	v_mfma_f32_32x32x16_bf16 v[2:17], v[180:183], v[50:53], v[2:17]
	v_cvt_pk_bf16_f32 v60, v62, v63
	v_cvt_pk_bf16_f32 v61, v64, v65
	v_max3_f32 v234, v66, v67, v68
	v_max3_f32 v235, v82, v83, v84
	v_max3_f32 v234, v234, v69, v70
	v_max3_f32 v235, v235, v85, v86
	v_mfma_f32_32x32x16_bf16 v[18:33], v[184:187], v[50:53], v[18:33]
	v_max3_f32 v234, v234, v71, v72
	v_max3_f32 v235, v235, v87, v88
	v_max3_f32 v234, v234, v73, v74
	v_max3_f32 v235, v235, v89, v90
	v_max3_f32 v234, v234, v75, v76
	v_max3_f32 v235, v235, v91, v92
	s_waitcnt lgkmcnt(2)
	v_mfma_f32_32x32x16_bf16 v[2:17], v[188:191], v[58:61], v[2:17]
	v_max3_f32 v234, v234, v77, v78
	v_max3_f32 v235, v235, v93, v94
	v_max3_f32 v234, v234, v79, v80
	v_max3_f32 v235, v235, v95, v96
	v_max3_f32 v234, v234, v81, v97
	v_max_f32_e32 v234, v234, v235
	v_mfma_f32_32x32x16_bf16 v[18:33], v[192:195], v[58:61], v[18:33]
	v_mov_b32_e32 v235, v234
	s_nop 1
	v_permlane32_swap_b32_e32 v234, v235
	v_max_f32_e32 v233, v234, v235
	v_cmp_lt_f32_e32 vcc, 4.0, v233
	s_cbranch_vccz .Lmls_nr_t0
	s_nop 15
	v_max_f32_e32 v234, 0, v233
	v_exp_f32_e64 v235, -v234
	v_add_f32_e32 v230, v230, v234
	v_sub_f32_e32 v66, v66, v234
	v_sub_f32_e32 v67, v67, v234
	v_sub_f32_e32 v68, v68, v234
	v_sub_f32_e32 v69, v69, v234
	v_sub_f32_e32 v70, v70, v234
	v_sub_f32_e32 v71, v71, v234
	v_sub_f32_e32 v72, v72, v234
	v_sub_f32_e32 v73, v73, v234
	v_sub_f32_e32 v74, v74, v234
	v_sub_f32_e32 v75, v75, v234
	v_sub_f32_e32 v76, v76, v234
	v_sub_f32_e32 v77, v77, v234
	v_sub_f32_e32 v78, v78, v234
	v_sub_f32_e32 v79, v79, v234
	v_sub_f32_e32 v80, v80, v234
	v_sub_f32_e32 v81, v81, v234
	v_sub_f32_e32 v82, v82, v234
	v_sub_f32_e32 v83, v83, v234
	v_sub_f32_e32 v84, v84, v234
	v_sub_f32_e32 v85, v85, v234
	v_sub_f32_e32 v86, v86, v234
	v_sub_f32_e32 v87, v87, v234
	v_sub_f32_e32 v88, v88, v234
	v_sub_f32_e32 v89, v89, v234
	v_sub_f32_e32 v90, v90, v234
	v_sub_f32_e32 v91, v91, v234
	v_sub_f32_e32 v92, v92, v234
	v_sub_f32_e32 v93, v93, v234
	v_sub_f32_e32 v94, v94, v234
	v_sub_f32_e32 v95, v95, v234
	v_sub_f32_e32 v96, v96, v234
	v_sub_f32_e32 v97, v97, v234
	v_mul_f32_e32 v231, v231, v235
	v_mul_f32_e32 v232, v232, v235
	v_mul_f32_e32 v2, v2, v235
	v_mul_f32_e32 v3, v3, v235
	v_mul_f32_e32 v4, v4, v235
	v_mul_f32_e32 v5, v5, v235
	v_mul_f32_e32 v6, v6, v235
	v_mul_f32_e32 v7, v7, v235
	v_mul_f32_e32 v8, v8, v235
	v_mul_f32_e32 v9, v9, v235
	v_mul_f32_e32 v10, v10, v235
	v_mul_f32_e32 v11, v11, v235
	v_mul_f32_e32 v12, v12, v235
	v_mul_f32_e32 v13, v13, v235
	v_mul_f32_e32 v14, v14, v235
	v_mul_f32_e32 v15, v15, v235
	v_mul_f32_e32 v16, v16, v235
	v_mul_f32_e32 v17, v17, v235
	v_mul_f32_e32 v18, v18, v235
	v_mul_f32_e32 v19, v19, v235
	v_mul_f32_e32 v20, v20, v235
	v_mul_f32_e32 v21, v21, v235
	v_mul_f32_e32 v22, v22, v235
	v_mul_f32_e32 v23, v23, v235
	v_mul_f32_e32 v24, v24, v235
	v_mul_f32_e32 v25, v25, v235
	v_mul_f32_e32 v26, v26, v235
	v_mul_f32_e32 v27, v27, v235
	v_mul_f32_e32 v28, v28, v235
	v_mul_f32_e32 v29, v29, v235
	v_mul_f32_e32 v30, v30, v235
	v_mul_f32_e32 v31, v31, v235
	v_mul_f32_e32 v32, v32, v235
	v_mul_f32_e32 v33, v33, v235
	v_sub_f32_e32 v122, 0, v230
	v_mov_b32_e32 v123, v122
	v_mov_b32_e32 v124, v122
	v_mov_b32_e32 v125, v122
	v_mov_b32_e32 v126, v122
	v_mov_b32_e32 v127, v122
	v_mov_b32_e32 v128, v122
	v_mov_b32_e32 v129, v122
	v_mov_b32_e32 v130, v122
	v_mov_b32_e32 v131, v122
	v_mov_b32_e32 v132, v122
	v_mov_b32_e32 v133, v122
	v_mov_b32_e32 v134, v122
	v_mov_b32_e32 v135, v122
	v_mov_b32_e32 v136, v122
	v_mov_b32_e32 v137, v122
.Lmls_nr_t0:
	ds_read_b128 v[138:141], v220 offset:26624
	ds_read_b128 v[142:145], v220 offset:33280
	ds_read_b128 v[146:149], v220 offset:26656
	ds_read_b128 v[150:153], v220 offset:33312
	ds_read_b128 v[154:157], v220 offset:26688
	ds_read_b128 v[158:161], v220 offset:33344
	s_waitcnt lgkmcnt(6)
	s_barrier
	v_exp_f32_e32 v66, v66
	v_exp_f32_e32 v67, v67
	v_exp_f32_e32 v68, v68
	v_exp_f32_e32 v69, v69
	s_waitcnt lgkmcnt(4)
	v_mfma_f32_32x32x16_bf16 v[34:49], v[138:141], v[98:101], v[122:137]
	ds_read_b128 v[138:141], v220 offset:26720
	v_add_f32_e32 v231, v231, v66
	v_add_f32_e32 v232, v232, v67
	v_exp_f32_e32 v70, v70
	v_exp_f32_e32 v71, v71
	v_mfma_f32_32x32x16_bf16 v[50:65], v[142:145], v[98:101], v[122:137]
	ds_read_b128 v[142:145], v220 offset:33376
	v_add_f32_e32 v231, v231, v68
	v_add_f32_e32 v232, v232, v69
	v_exp_f32_e32 v72, v72
	v_exp_f32_e32 v73, v73
	v_add_f32_e32 v231, v231, v70
	s_waitcnt lgkmcnt(4)
	v_mfma_f32_32x32x16_bf16 v[34:49], v[146:149], v[102:105], v[34:49]
	ds_read_b128 v[146:149], v220 offset:26752
	v_add_f32_e32 v232, v232, v71
	v_add_f32_e32 v231, v231, v72
	v_add_f32_e32 v232, v232, v73
	v_cvt_pk_bf16_f32 v66, v66, v67
	v_cvt_pk_bf16_f32 v67, v68, v69
	v_mfma_f32_32x32x16_bf16 v[50:65], v[150:153], v[102:105], v[50:65]
	ds_read_b128 v[150:153], v220 offset:33408
	v_cvt_pk_bf16_f32 v68, v70, v71
	v_cvt_pk_bf16_f32 v69, v72, v73
	v_exp_f32_e32 v74, v74
	v_exp_f32_e32 v75, v75
	v_exp_f32_e32 v76, v76
	s_waitcnt lgkmcnt(4)
	v_mfma_f32_32x32x16_bf16 v[34:49], v[154:157], v[106:109], v[34:49]
	ds_read_b128 v[154:157], v220 offset:26784
	v_exp_f32_e32 v77, v77
	v_add_f32_e32 v231, v231, v74
	v_add_f32_e32 v232, v232, v75
	v_exp_f32_e32 v78, v78
	v_mfma_f32_32x32x16_bf16 v[50:65], v[158:161], v[106:109], v[50:65]
	ds_read_b128 v[158:161], v220 offset:33440
	v_exp_f32_e32 v79, v79
	v_add_f32_e32 v231, v231, v76
	v_add_f32_e32 v232, v232, v77
	v_exp_f32_e32 v80, v80
	s_waitcnt lgkmcnt(4)
	v_mfma_f32_32x32x16_bf16 v[34:49], v[138:141], v[110:113], v[34:49]
	ds_read_b128 v[162:165], v221 offset:9216
	v_exp_f32_e32 v81, v81
	v_add_f32_e32 v231, v231, v78
	v_add_f32_e32 v232, v232, v79
	v_add_f32_e32 v231, v231, v80
	v_add_f32_e32 v232, v232, v81
	v_mfma_f32_32x32x16_bf16 v[50:65], v[142:145], v[110:113], v[50:65]
	ds_read_b128 v[166:169], v221 offset:13824
	v_cvt_pk_bf16_f32 v74, v74, v75
	v_cvt_pk_bf16_f32 v75, v76, v77
	v_cvt_pk_bf16_f32 v76, v78, v79
	v_cvt_pk_bf16_f32 v77, v80, v81
	v_exp_f32_e32 v82, v82
	v_exp_f32_e32 v83, v83
	s_waitcnt lgkmcnt(4)
	v_mfma_f32_32x32x16_bf16 v[34:49], v[146:149], v[114:117], v[34:49]
	ds_read_b128 v[170:173], v221 offset:9248
	v_exp_f32_e32 v84, v84
	v_exp_f32_e32 v85, v85
	v_add_f32_e32 v231, v231, v82
	v_mfma_f32_32x32x16_bf16 v[50:65], v[150:153], v[114:117], v[50:65]
	ds_read_b128 v[174:177], v221 offset:13856
	v_add_f32_e32 v232, v232, v83
	v_exp_f32_e32 v86, v86
	v_exp_f32_e32 v87, v87
	v_add_f32_e32 v231, v231, v84
	v_add_f32_e32 v232, v232, v85
	s_waitcnt lgkmcnt(4)
	v_mfma_f32_32x32x16_bf16 v[34:49], v[154:157], v[118:121], v[34:49]
	ds_read_b128 v[180:183], v221 offset:9280
	v_exp_f32_e32 v88, v88
	v_exp_f32_e32 v89, v89
	v_add_f32_e32 v231, v231, v86
	v_add_f32_e32 v232, v232, v87
	v_mfma_f32_32x32x16_bf16 v[50:65], v[158:161], v[118:121], v[50:65]
	ds_read_b128 v[184:187], v221 offset:13888
	v_add_f32_e32 v231, v231, v88
	v_add_f32_e32 v232, v232, v89
	v_cvt_pk_bf16_f32 v82, v82, v83
	v_cvt_pk_bf16_f32 v83, v84, v85
	v_cvt_pk_bf16_f32 v84, v86, v87
	v_cvt_pk_bf16_f32 v85, v88, v89
	s_waitcnt lgkmcnt(4)
	v_mfma_f32_32x32x16_bf16 v[2:17], v[162:165], v[66:69], v[2:17]
	ds_read_b128 v[188:191], v221 offset:9312
	v_exp_f32_e32 v90, v90
	v_exp_f32_e32 v91, v91
	v_exp_f32_e32 v92, v92
	v_exp_f32_e32 v93, v93
	v_mfma_f32_32x32x16_bf16 v[18:33], v[166:169], v[66:69], v[18:33]
	ds_read_b128 v[192:195], v221 offset:13920
	v_add_f32_e32 v231, v231, v90
	v_add_f32_e32 v232, v232, v91
	v_exp_f32_e32 v94, v94
	v_exp_f32_e32 v95, v95
	s_waitcnt lgkmcnt(4)
	v_mfma_f32_32x32x16_bf16 v[2:17], v[170:173], v[74:77], v[2:17]
	v_add_f32_e32 v231, v231, v92
	v_add_f32_e32 v232, v232, v93
	v_exp_f32_e32 v96, v96
	v_exp_f32_e32 v97, v97
	v_mfma_f32_32x32x16_bf16 v[18:33], v[174:177], v[74:77], v[18:33]
	s_waitcnt vmcnt(0)
	ds_write_b64 v225, v[212:213] offset:27648
	ds_write_b64 v225, v[214:215] offset:27664
	v_add_f32_e32 v231, v231, v94
	v_add_f32_e32 v232, v232, v95
	v_add_f32_e32 v231, v231, v96
	v_add_f32_e32 v232, v232, v97
	v_cvt_pk_bf16_f32 v90, v90, v91
	v_cvt_pk_bf16_f32 v91, v92, v93
	s_waitcnt lgkmcnt(4)
	v_mfma_f32_32x32x16_bf16 v[2:17], v[180:183], v[82:85], v[2:17]
	v_cvt_pk_bf16_f32 v92, v94, v95
	v_cvt_pk_bf16_f32 v93, v96, v97
	v_max3_f32 v234, v34, v35, v36
	v_max3_f32 v235, v50, v51, v52
	v_max3_f32 v234, v234, v37, v38
	v_max3_f32 v235, v235, v53, v54
	v_mfma_f32_32x32x16_bf16 v[18:33], v[184:187], v[82:85], v[18:33]
	v_max3_f32 v234, v234, v39, v40
	v_max3_f32 v235, v235, v55, v56
	v_max3_f32 v234, v234, v41, v42
	v_max3_f32 v235, v235, v57, v58
	v_max3_f32 v234, v234, v43, v44
	v_max3_f32 v235, v235, v59, v60
	s_waitcnt lgkmcnt(2)
	v_mfma_f32_32x32x16_bf16 v[2:17], v[188:191], v[90:93], v[2:17]
	v_max3_f32 v234, v234, v45, v46
	v_max3_f32 v235, v235, v61, v62
	v_max3_f32 v234, v234, v47, v48
	v_max3_f32 v235, v235, v63, v64
	v_max3_f32 v234, v234, v49, v65
	v_max_f32_e32 v234, v234, v235
	v_mfma_f32_32x32x16_bf16 v[18:33], v[192:195], v[90:93], v[18:33]
	v_mov_b32_e32 v235, v234
	s_nop 1
	v_permlane32_swap_b32_e32 v234, v235
	v_max_f32_e32 v233, v234, v235
	v_cmp_lt_f32_e32 vcc, 4.0, v233
	s_cbranch_vccz .Lmls_nr_t1
	s_nop 15
	v_max_f32_e32 v234, 0, v233
	v_exp_f32_e64 v235, -v234
	v_add_f32_e32 v230, v230, v234
	v_sub_f32_e32 v34, v34, v234
	v_sub_f32_e32 v35, v35, v234
	v_sub_f32_e32 v36, v36, v234
	v_sub_f32_e32 v37, v37, v234
	v_sub_f32_e32 v38, v38, v234
	v_sub_f32_e32 v39, v39, v234
	v_sub_f32_e32 v40, v40, v234
	v_sub_f32_e32 v41, v41, v234
	v_sub_f32_e32 v42, v42, v234
	v_sub_f32_e32 v43, v43, v234
	v_sub_f32_e32 v44, v44, v234
	v_sub_f32_e32 v45, v45, v234
	v_sub_f32_e32 v46, v46, v234
	v_sub_f32_e32 v47, v47, v234
	v_sub_f32_e32 v48, v48, v234
	v_sub_f32_e32 v49, v49, v234
	v_sub_f32_e32 v50, v50, v234
	v_sub_f32_e32 v51, v51, v234
	v_sub_f32_e32 v52, v52, v234
	v_sub_f32_e32 v53, v53, v234
	v_sub_f32_e32 v54, v54, v234
	v_sub_f32_e32 v55, v55, v234
	v_sub_f32_e32 v56, v56, v234
	v_sub_f32_e32 v57, v57, v234
	v_sub_f32_e32 v58, v58, v234
	v_sub_f32_e32 v59, v59, v234
	v_sub_f32_e32 v60, v60, v234
	v_sub_f32_e32 v61, v61, v234
	v_sub_f32_e32 v62, v62, v234
	v_sub_f32_e32 v63, v63, v234
	v_sub_f32_e32 v64, v64, v234
	v_sub_f32_e32 v65, v65, v234
	v_mul_f32_e32 v231, v231, v235
	v_mul_f32_e32 v232, v232, v235
	v_mul_f32_e32 v2, v2, v235
	v_mul_f32_e32 v3, v3, v235
	v_mul_f32_e32 v4, v4, v235
	v_mul_f32_e32 v5, v5, v235
	v_mul_f32_e32 v6, v6, v235
	v_mul_f32_e32 v7, v7, v235
	v_mul_f32_e32 v8, v8, v235
	v_mul_f32_e32 v9, v9, v235
	v_mul_f32_e32 v10, v10, v235
	v_mul_f32_e32 v11, v11, v235
	v_mul_f32_e32 v12, v12, v235
	v_mul_f32_e32 v13, v13, v235
	v_mul_f32_e32 v14, v14, v235
	v_mul_f32_e32 v15, v15, v235
	v_mul_f32_e32 v16, v16, v235
	v_mul_f32_e32 v17, v17, v235
	v_mul_f32_e32 v18, v18, v235
	v_mul_f32_e32 v19, v19, v235
	v_mul_f32_e32 v20, v20, v235
	v_mul_f32_e32 v21, v21, v235
	v_mul_f32_e32 v22, v22, v235
	v_mul_f32_e32 v23, v23, v235
	v_mul_f32_e32 v24, v24, v235
	v_mul_f32_e32 v25, v25, v235
	v_mul_f32_e32 v26, v26, v235
	v_mul_f32_e32 v27, v27, v235
	v_mul_f32_e32 v28, v28, v235
	v_mul_f32_e32 v29, v29, v235
	v_mul_f32_e32 v30, v30, v235
	v_mul_f32_e32 v31, v31, v235
	v_mul_f32_e32 v32, v32, v235
	v_mul_f32_e32 v33, v33, v235
	v_sub_f32_e32 v122, 0, v230
	v_mov_b32_e32 v123, v122
	v_mov_b32_e32 v124, v122
	v_mov_b32_e32 v125, v122
	v_mov_b32_e32 v126, v122
	v_mov_b32_e32 v127, v122
	v_mov_b32_e32 v128, v122
	v_mov_b32_e32 v129, v122
	v_mov_b32_e32 v130, v122
	v_mov_b32_e32 v131, v122
	v_mov_b32_e32 v132, v122
	v_mov_b32_e32 v133, v122
	v_mov_b32_e32 v134, v122
	v_mov_b32_e32 v135, v122
	v_mov_b32_e32 v136, v122
	v_mov_b32_e32 v137, v122
.Lmls_nr_t1:
	ds_read_b128 v[138:141], v220 offset:39936
	ds_read_b128 v[142:145], v220 offset:46592
	ds_read_b128 v[146:149], v220 offset:39968
	ds_read_b128 v[150:153], v220 offset:46624
	ds_read_b128 v[154:157], v220 offset:40000
	ds_read_b128 v[158:161], v220 offset:46656
	s_waitcnt lgkmcnt(6)
	s_barrier
	global_load_dwordx2 v[200:201], v236, s[14:15] offset:0
	global_load_dwordx2 v[202:203], v236, s[14:15] offset:16
	global_load_dwordx2 v[204:205], v236, s[14:15] offset:32
	global_load_dwordx2 v[206:207], v236, s[14:15] offset:48
	global_load_dwordx2 v[208:209], v236, s[14:15] offset:64
	global_load_dwordx2 v[210:211], v236, s[14:15] offset:80
	global_load_dwordx2 v[212:213], v236, s[14:15] offset:96
	global_load_dwordx2 v[214:215], v236, s[14:15] offset:112
	v_exp_f32_e32 v34, v34
	v_exp_f32_e32 v35, v35
	v_exp_f32_e32 v36, v36
	v_exp_f32_e32 v37, v37
	s_waitcnt lgkmcnt(4)
	v_mfma_f32_32x32x16_bf16 v[66:81], v[138:141], v[98:101], v[122:137]
	ds_read_b128 v[138:141], v220 offset:40032
	v_add_f32_e32 v231, v231, v34
	v_add_f32_e32 v232, v232, v35
	v_exp_f32_e32 v38, v38
	v_exp_f32_e32 v39, v39
	v_mfma_f32_32x32x16_bf16 v[82:97], v[142:145], v[98:101], v[122:137]
	ds_read_b128 v[142:145], v220 offset:46688
	v_add_f32_e32 v231, v231, v36
	v_add_f32_e32 v232, v232, v37
	v_exp_f32_e32 v40, v40
	v_exp_f32_e32 v41, v41
	v_add_f32_e32 v231, v231, v38
	s_waitcnt lgkmcnt(4)
	v_mfma_f32_32x32x16_bf16 v[66:81], v[146:149], v[102:105], v[66:81]
	ds_read_b128 v[146:149], v220 offset:40064
	v_add_f32_e32 v232, v232, v39
	v_add_f32_e32 v231, v231, v40
	v_add_f32_e32 v232, v232, v41
	v_cvt_pk_bf16_f32 v34, v34, v35
	v_cvt_pk_bf16_f32 v35, v36, v37
	v_mfma_f32_32x32x16_bf16 v[82:97], v[150:153], v[102:105], v[82:97]
	ds_read_b128 v[150:153], v220 offset:46720
	v_cvt_pk_bf16_f32 v36, v38, v39
	v_cvt_pk_bf16_f32 v37, v40, v41
	v_exp_f32_e32 v42, v42
	v_exp_f32_e32 v43, v43
	v_exp_f32_e32 v44, v44
	s_waitcnt lgkmcnt(4)
	v_mfma_f32_32x32x16_bf16 v[66:81], v[154:157], v[106:109], v[66:81]
	ds_read_b128 v[154:157], v220 offset:40096
	v_exp_f32_e32 v45, v45
	v_add_f32_e32 v231, v231, v42
	v_add_f32_e32 v232, v232, v43
	v_exp_f32_e32 v46, v46
	v_mfma_f32_32x32x16_bf16 v[82:97], v[158:161], v[106:109], v[82:97]
	ds_read_b128 v[158:161], v220 offset:46752
	v_exp_f32_e32 v47, v47
	v_add_f32_e32 v231, v231, v44
	v_add_f32_e32 v232, v232, v45
	v_exp_f32_e32 v48, v48
	s_waitcnt lgkmcnt(4)
	v_mfma_f32_32x32x16_bf16 v[66:81], v[138:141], v[110:113], v[66:81]
	ds_read_b128 v[162:165], v221 offset:18432
	v_exp_f32_e32 v49, v49
	v_add_f32_e32 v231, v231, v46
	v_add_f32_e32 v232, v232, v47
	v_add_f32_e32 v231, v231, v48
	v_add_f32_e32 v232, v232, v49
	v_mfma_f32_32x32x16_bf16 v[82:97], v[142:145], v[110:113], v[82:97]
	ds_read_b128 v[166:169], v221 offset:23040
	v_cvt_pk_bf16_f32 v42, v42, v43
	v_cvt_pk_bf16_f32 v43, v44, v45
	v_cvt_pk_bf16_f32 v44, v46, v47
	v_cvt_pk_bf16_f32 v45, v48, v49
	v_exp_f32_e32 v50, v50
	v_exp_f32_e32 v51, v51
	s_waitcnt lgkmcnt(4)
	v_mfma_f32_32x32x16_bf16 v[66:81], v[146:149], v[114:117], v[66:81]
	ds_read_b128 v[170:173], v221 offset:18464
	v_exp_f32_e32 v52, v52
	v_exp_f32_e32 v53, v53
	v_add_f32_e32 v231, v231, v50
	v_mfma_f32_32x32x16_bf16 v[82:97], v[150:153], v[114:117], v[82:97]
	ds_read_b128 v[174:177], v221 offset:23072
	v_add_f32_e32 v232, v232, v51
	v_exp_f32_e32 v54, v54
	v_exp_f32_e32 v55, v55
	v_add_f32_e32 v231, v231, v52
	v_add_f32_e32 v232, v232, v53
	s_waitcnt lgkmcnt(4)
	v_mfma_f32_32x32x16_bf16 v[66:81], v[154:157], v[118:121], v[66:81]
	ds_read_b128 v[180:183], v221 offset:18496
	v_exp_f32_e32 v56, v56
	v_exp_f32_e32 v57, v57
	v_add_f32_e32 v231, v231, v54
	v_add_f32_e32 v232, v232, v55
	v_mfma_f32_32x32x16_bf16 v[82:97], v[158:161], v[118:121], v[82:97]
	ds_read_b128 v[184:187], v221 offset:23104
	v_add_f32_e32 v231, v231, v56
	v_add_f32_e32 v232, v232, v57
	v_cvt_pk_bf16_f32 v50, v50, v51
	v_cvt_pk_bf16_f32 v51, v52, v53
	v_cvt_pk_bf16_f32 v52, v54, v55
	v_cvt_pk_bf16_f32 v53, v56, v57
	s_waitcnt lgkmcnt(4)
	v_mfma_f32_32x32x16_bf16 v[2:17], v[162:165], v[34:37], v[2:17]
	ds_read_b128 v[188:191], v221 offset:18528
	v_exp_f32_e32 v58, v58
	v_exp_f32_e32 v59, v59
	v_exp_f32_e32 v60, v60
	v_exp_f32_e32 v61, v61
	v_mfma_f32_32x32x16_bf16 v[18:33], v[166:169], v[34:37], v[18:33]
	ds_read_b128 v[192:195], v221 offset:23136
	v_add_f32_e32 v231, v231, v58
	v_add_f32_e32 v232, v232, v59
	v_exp_f32_e32 v62, v62
	v_exp_f32_e32 v63, v63
	s_waitcnt lgkmcnt(4)
	v_mfma_f32_32x32x16_bf16 v[2:17], v[170:173], v[42:45], v[2:17]
	v_add_f32_e32 v231, v231, v60
	v_add_f32_e32 v232, v232, v61
	v_exp_f32_e32 v64, v64
	v_exp_f32_e32 v65, v65
	v_mfma_f32_32x32x16_bf16 v[18:33], v[174:177], v[42:45], v[18:33]
	v_add_f32_e32 v231, v231, v62
	v_add_f32_e32 v232, v232, v63
	v_add_f32_e32 v231, v231, v64
	v_add_f32_e32 v232, v232, v65
	v_cvt_pk_bf16_f32 v58, v58, v59
	v_cvt_pk_bf16_f32 v59, v60, v61
	s_waitcnt lgkmcnt(2)
	v_mfma_f32_32x32x16_bf16 v[2:17], v[180:183], v[50:53], v[2:17]
	v_cvt_pk_bf16_f32 v60, v62, v63
	v_cvt_pk_bf16_f32 v61, v64, v65
	v_max3_f32 v234, v66, v67, v68
	v_max3_f32 v235, v82, v83, v84
	v_max3_f32 v234, v234, v69, v70
	v_max3_f32 v235, v235, v85, v86
	v_mfma_f32_32x32x16_bf16 v[18:33], v[184:187], v[50:53], v[18:33]
	v_max3_f32 v234, v234, v71, v72
	v_max3_f32 v235, v235, v87, v88
	v_max3_f32 v234, v234, v73, v74
	v_max3_f32 v235, v235, v89, v90
	v_max3_f32 v234, v234, v75, v76
	v_max3_f32 v235, v235, v91, v92
	s_waitcnt lgkmcnt(0)
	v_mfma_f32_32x32x16_bf16 v[2:17], v[188:191], v[58:61], v[2:17]
	v_max3_f32 v234, v234, v77, v78
	v_max3_f32 v235, v235, v93, v94
	v_max3_f32 v234, v234, v79, v80
	v_max3_f32 v235, v235, v95, v96
	v_max3_f32 v234, v234, v81, v97
	v_max_f32_e32 v234, v234, v235
	v_mfma_f32_32x32x16_bf16 v[18:33], v[192:195], v[58:61], v[18:33]
	v_mov_b32_e32 v235, v234
	s_nop 1
	v_permlane32_swap_b32_e32 v234, v235
	v_max_f32_e32 v233, v234, v235
	v_cmp_lt_f32_e32 vcc, 4.0, v233
	s_cbranch_vccz .Lmls_nr_t2
	s_nop 15
	v_max_f32_e32 v234, 0, v233
	v_exp_f32_e64 v235, -v234
	v_add_f32_e32 v230, v230, v234
	v_sub_f32_e32 v66, v66, v234
	v_sub_f32_e32 v67, v67, v234
	v_sub_f32_e32 v68, v68, v234
	v_sub_f32_e32 v69, v69, v234
	v_sub_f32_e32 v70, v70, v234
	v_sub_f32_e32 v71, v71, v234
	v_sub_f32_e32 v72, v72, v234
	v_sub_f32_e32 v73, v73, v234
	v_sub_f32_e32 v74, v74, v234
	v_sub_f32_e32 v75, v75, v234
	v_sub_f32_e32 v76, v76, v234
	v_sub_f32_e32 v77, v77, v234
	v_sub_f32_e32 v78, v78, v234
	v_sub_f32_e32 v79, v79, v234
	v_sub_f32_e32 v80, v80, v234
	v_sub_f32_e32 v81, v81, v234
	v_sub_f32_e32 v82, v82, v234
	v_sub_f32_e32 v83, v83, v234
	v_sub_f32_e32 v84, v84, v234
	v_sub_f32_e32 v85, v85, v234
	v_sub_f32_e32 v86, v86, v234
	v_sub_f32_e32 v87, v87, v234
	v_sub_f32_e32 v88, v88, v234
	v_sub_f32_e32 v89, v89, v234
	v_sub_f32_e32 v90, v90, v234
	v_sub_f32_e32 v91, v91, v234
	v_sub_f32_e32 v92, v92, v234
	v_sub_f32_e32 v93, v93, v234
	v_sub_f32_e32 v94, v94, v234
	v_sub_f32_e32 v95, v95, v234
	v_sub_f32_e32 v96, v96, v234
	v_sub_f32_e32 v97, v97, v234
	v_mul_f32_e32 v231, v231, v235
	v_mul_f32_e32 v232, v232, v235
	v_mul_f32_e32 v2, v2, v235
	v_mul_f32_e32 v3, v3, v235
	v_mul_f32_e32 v4, v4, v235
	v_mul_f32_e32 v5, v5, v235
	v_mul_f32_e32 v6, v6, v235
	v_mul_f32_e32 v7, v7, v235
	v_mul_f32_e32 v8, v8, v235
	v_mul_f32_e32 v9, v9, v235
	v_mul_f32_e32 v10, v10, v235
	v_mul_f32_e32 v11, v11, v235
	v_mul_f32_e32 v12, v12, v235
	v_mul_f32_e32 v13, v13, v235
	v_mul_f32_e32 v14, v14, v235
	v_mul_f32_e32 v15, v15, v235
	v_mul_f32_e32 v16, v16, v235
	v_mul_f32_e32 v17, v17, v235
	v_mul_f32_e32 v18, v18, v235
	v_mul_f32_e32 v19, v19, v235
	v_mul_f32_e32 v20, v20, v235
	v_mul_f32_e32 v21, v21, v235
	v_mul_f32_e32 v22, v22, v235
	v_mul_f32_e32 v23, v23, v235
	v_mul_f32_e32 v24, v24, v235
	v_mul_f32_e32 v25, v25, v235
	v_mul_f32_e32 v26, v26, v235
	v_mul_f32_e32 v27, v27, v235
	v_mul_f32_e32 v28, v28, v235
	v_mul_f32_e32 v29, v29, v235
	v_mul_f32_e32 v30, v30, v235
	v_mul_f32_e32 v31, v31, v235
	v_mul_f32_e32 v32, v32, v235
	v_mul_f32_e32 v33, v33, v235
	v_sub_f32_e32 v122, 0, v230
	v_mov_b32_e32 v123, v122
	v_mov_b32_e32 v124, v122
	v_mov_b32_e32 v125, v122
	v_mov_b32_e32 v126, v122
	v_mov_b32_e32 v127, v122
	v_mov_b32_e32 v128, v122
	v_mov_b32_e32 v129, v122
	v_mov_b32_e32 v130, v122
	v_mov_b32_e32 v131, v122
	v_mov_b32_e32 v132, v122
	v_mov_b32_e32 v133, v122
	v_mov_b32_e32 v134, v122
	v_mov_b32_e32 v135, v122
	v_mov_b32_e32 v136, v122
	v_mov_b32_e32 v137, v122
